# next tile's first-fragment LDS reads issued ahead of the SwiGLU epilogues (and at the end of the first-unit prologue) instead of at the head of the first K iteration; plus s_nop 0 restored at 4 sites
# baseline (speedup 1.0000x reference)
; template <class Epi, class Sched, bool ALIGN_EPI = false, bool SP2 = false>
; __device__ __forceinline__ void gemm_phase(PG8_LAS unsigned char* lds, const Gemm g, const Sched& S, const Epi& E) {
;     ...
;     for (int i = 0; i < 2; ++i) { int R, C; stage_rc(tid * 16 + i * 8192, R, C); const int Rb = Epi::PERM ? ((R & ~31) + perm32(R & 31)) : R;
;         voffA[i] = (unsigned)(R * K + C) * 2u; voffB[i] = (unsigned)(Rb * K + C) * 2u; }
;     const size_t kstep = (size_t)(BK * 2);
;     const size_t hstep = (size_t)HALF * K * 2;
;     const size_t tstep = 2 * hstep;
;     const unsigned ldsw = (unsigned)wid * 1024u;
;     const int aoff = lds_byte(wr * 64 + fr, fq * 8), boff = lds_byte(wc * 32 + fr, fq * 8);
;     ...
;         PG8_STAGE(PG8_SB(0, 0), cB, voffB); PG8_STAGE(PG8_SB(0, 1), cB + hstep, voffB); PG8_STAGE(PG8_SA(0, 0), cA, voffA); PG8_STAGE(PG8_SA(0, 1), cA + hstep, voffA);
;         if (wr == 1) PG8_BAR;
;         PG8_WAIT_V(2); PG8_BAR;
;         PG8_STAGE(PG8_SB(1, 0), cB + kstep, voffB); PG8_STAGE(PG8_SA(1, 0), cA + kstep, voffA); PG8_STAGE(PG8_SB(1, 1), cB + hstep + kstep, voffB);
;         PG8_WAIT_V(6); PG8_BAR;
;     } else {
;         PG8_STAGE(PG8_SB(0, 0), cB, voffB); PG8_STAGE(PG8_SA(0, 0), cA, voffA); PG8_STAGE(PG8_SB(0, 1), cB + hstep, voffB); PG8_STAGE(PG8_SA(0, 1), cA + hstep, voffA);
;         if (wr == 1) PG8_BAR;
;         PG8_WAIT_V(4); PG8_BAR;
;         PG8_STAGE(PG8_SB(1, 0), cB + kstep, voffB); PG8_STAGE(PG8_SA(1, 0), cA + kstep, voffA); PG8_STAGE(PG8_SB(1, 1), cB + hstep + kstep, voffB);
;         PG8_WAIT_V(6); PG8_BAR;
;     }
;     for (;;) {
;         const bool has_next = S.next(ui + 1, nxt);
;         const char* nA = has_next ? (const char*)g.A + (size_t)nxt.pm * tstep : cA; const char* nB = has_next ? (const char*)g.Bt + (size_t)nxt.pn * tstep : cB;
;         for (int t = 0; t < nt; t += 2) {
;             const bool last = (t == nt - 2);
;             const char* a1 = cA + (size_t)(t + 1) * kstep;
;             const char* a2 = last ? nA : cA + (size_t)(t + 2) * kstep; const char* b2 = last ? nB : cB + (size_t)(t + 2) * kstep;
;             const char* a3 = a2 + kstep; const char* b3 = b2 + kstep;
;             if (last && has_next) S.a_ready(nxt);
;             if constexpr (SP2) {
;             PG8_LDB(B0, 0, 0); PG8_LDB(B1, 0, 1); PG8_SCHED; PG8_LDA(At, 0, 0); PG8_STAGE(PG8_SA(1, 1), a1 + hstep, voffA);
.LBB0_79:
	s_lshl_b32 s7, s7, 5
	s_and_b32 s11, s7, 0x60
	s_add_i32 m0, s27, 0x18000
	v_lshl_add_u64 v[10:11], v[10:11], 0, s[36:37]
	s_lshl_b32 s10, s8, 13
	s_lshl_b32 s7, s11, 7
	s_waitcnt vmcnt(2)
	s_barrier
	global_load_lds_dwordx4 v[10:11], off
	v_lshl_add_u64 v[8:9], v[8:9], 0, s[36:37]
	s_add_i32 m0, s27, 0x1a000
	s_add_i32 s31, s27, 0x8000
	s_add_i32 s34, s27, 0xa000
	global_load_lds_dwordx4 v[8:9], off
	v_lshl_add_u64 v[4:5], v[4:5], 0, s[36:37]
	s_mov_b32 m0, s31
	s_add_u32 s8, s20, 0x80080
	global_load_lds_dwordx4 v[4:5], off
	v_lshl_add_u64 v[4:5], v[6:7], 0, s[36:37]
	s_mov_b32 m0, s34
	s_addc_u32 s9, s21, 0
	global_load_lds_dwordx4 v[4:5], off
	s_add_i32 m0, s27, 0x1c000
	v_lshl_add_u64 v[4:5], s[8:9], 0, v[2:3]
	global_load_lds_dwordx4 v[4:5], off
	v_lshl_add_u64 v[4:5], s[8:9], 0, v[0:1]
	s_add_i32 m0, s27, 0x1e000
	v_or_b32_e32 v152, s6, v15
	global_load_lds_dwordx4 v[4:5], off
	v_lshrrev_b32_e32 v4, 1, v13
	v_and_b32_e32 v4, 24, v4
	s_sext_i32_i16 s17, s2
	v_lshlrev_b32_e32 v5, 6, v152
	v_lshlrev_b32_e32 v6, 1, v4
	s_movk_i32 s2, 0x3c0
	v_lshlrev_b32_e32 v7, 2, v152
	v_and_or_b32 v5, v5, s2, v6
	v_and_b32_e32 v7, 32, v7
	v_bitop3_b32 v5, v5, s10, v7 bitop3:0xde
	v_lshlrev_b32_e32 v7, 2, v15
	v_or_b32_e32 v154, s11, v4
	v_lshlrev_b32_e32 v4, 15, v18
	v_lshl_or_b32 v6, v15, 6, v6
	v_and_b32_e32 v7, 32, v7
	v_and_b32_e32 v4, 0xffff0000, v4
	v_bitop3_b32 v153, v6, s7, v7 bitop3:0xde
	v_lshl_add_u32 v4, v17, 12, v4
	v_and_b32_e32 v6, 1, v18
	v_lshl_or_b32 v4, v6, 6, v4
	v_lshl_add_u32 v136, v19, 1, v4
	v_lshlrev_b32_e32 v4, 15, v12
	v_and_b32_e32 v4, 0xffff0000, v4
	s_waitcnt vmcnt(6)
	v_lshl_add_u32 v4, v14, 12, v4
	v_and_b32_e32 v6, 1, v12
	s_cmpk_lt_u32 s3, 0x100
	v_lshl_or_b32 v4, v6, 6, v4
	s_cselect_b64 s[6:7], -1, 0
	v_mov_b32_e32 v137, v3
	v_lshl_add_u32 v138, v16, 1, v4
	v_mov_b32_e32 v139, v3
	s_mov_b32 s35, 0
	v_add_u32_e32 v155, 0, v5
	s_barrier
	v_add_u32_e32 v166, 0x10000, v153
	ds_read_b128 v[184:187], v166
	ds_read_b128 v[188:191], v166 offset:1024
	ds_read_b128 v[192:195], v166 offset:2048
	ds_read_b128 v[196:199], v166 offset:3072
	v_add_u32_e32 v167, 0x14000, v153
	ds_read_b128 v[200:203], v167
	ds_read_b128 v[204:207], v167 offset:1024
	ds_read_b128 v[208:211], v167 offset:2048
	ds_read_b128 v[212:215], v167 offset:3072
	ds_read_b128 v[216:219], v155
	ds_read_b128 v[220:223], v155 offset:1024
	ds_read_b128 v[224:227], v155 offset:2048
	ds_read_b128 v[228:231], v155 offset:3072
	ds_read_b128 v[232:235], v155 offset:4096
	ds_read_b128 v[236:239], v155 offset:5120
	ds_read_b128 v[240:243], v155 offset:6144
	ds_read_b128 v[244:247], v155 offset:7168
	s_branch .LBB0_82

; #define PG8_STAGE(bufoff, gbase, voff) do { _Pragma("unroll") for (int _i = 0; _i < 2; ++_i) \
;         __builtin_amdgcn_global_load_lds((const unsigned*)((const char*)(gbase) + (voff)[_i]), (PG8_LAS unsigned*)(lds + (bufoff) + ldsw + _i * 8192), 16, 0, 0); } while (0)
; #define PG8_LDA(dst, b, h) do { _Pragma("unroll") for (int m = 0; m < 4; ++m) _Pragma("unroll") for (int k = 0; k < 2; ++k) dst[m][k] = *(const PG8_LAS bf16x8*)(lds + PG8_SA(b, h) + aoff + m * 2048 + k * 1024); } while (0)
; #define PG8_LDB(dst, b, h) do { _Pragma("unroll") for (int n = 0; n < 2; ++n) _Pragma("unroll") for (int k = 0; k < 2; ++k) dst[n][k] = *(const PG8_LAS bf16x8*)(lds + PG8_SB(b, h) + boff + n * 2048 + k * 1024); } while (0)
; #define PG8_WAIT_V(n) asm volatile("s_waitcnt vmcnt(" #n ")" ::: "memory")
; #define PG8_WAIT_L(n) asm volatile("s_waitcnt lgkmcnt(" #n ")" ::: "memory")
; #define PG8_BAR __builtin_amdgcn_s_barrier()
; #define PG8_SCHED __builtin_amdgcn_sched_barrier(0)
; template <class Epi, class Sched, bool ALIGN_EPI = false, bool SP2 = false>
; __device__ __forceinline__ void gemm_phase(PG8_LAS unsigned char* lds, const Gemm g, const Sched& S, const Epi& E) {
;     ...
;         const bool has_next = S.next(ui + 1, nxt);
;         const char* nA = has_next ? (const char*)g.A + (size_t)nxt.pm * tstep : cA; const char* nB = has_next ? (const char*)g.Bt + (size_t)nxt.pn * tstep : cB;
;         for (int t = 0; t < nt; t += 2) {
;             const bool last = (t == nt - 2);
;             const char* a1 = cA + (size_t)(t + 1) * kstep;
;             const char* a2 = last ? nA : cA + (size_t)(t + 2) * kstep; const char* b2 = last ? nB : cB + (size_t)(t + 2) * kstep;
;             const char* a3 = a2 + kstep; const char* b3 = b2 + kstep;
;             if (last && has_next) S.a_ready(nxt);
;             if constexpr (SP2) {
;             PG8_LDB(B0, 0, 0); PG8_LDB(B1, 0, 1); PG8_SCHED; PG8_LDA(At, 0, 0); PG8_STAGE(PG8_SA(1, 1), a1 + hstep, voffA);
;             PG8_WAIT_V(8); PG8_WAIT_L(0); PG8_BAR; PG8_MMA(0, 0, At, B0); PG8_MMA(0, 1, At, B1); PG8_BAR; PG8_SCHED;
;             PG8_LDA(At, 0, 1); PG8_STAGE(PG8_SB(0, 0), b2, voffB); PG8_STAGE(PG8_SB(0, 1), b2 + hstep, voffB); PG8_STAGE(PG8_SA(0, 0), a2, voffA);
;             PG8_WAIT_V(8); PG8_WAIT_L(0); PG8_BAR; PG8_MMA(1, 0, At, B0); PG8_MMA(1, 1, At, B1); PG8_BAR; PG8_SCHED;
.LBB0_84:
	s_ashr_i32 s11, s10, 31
	s_lshl_b64 s[12:13], s[10:11], 20
	s_add_u32 s12, s46, s12
	s_addc_u32 s13, s47, s13
	s_and_b64 s[14:15], s[2:3], exec
	s_cselect_b32 s11, s13, s19
	s_cselect_b32 s42, s12, s18
	s_ashr_i32 s9, s8, 31
	s_lshl_b64 s[14:15], s[8:9], 20
	v_readlane_b32 s9, v255, 30
	s_add_u32 s14, s9, s14
	v_readlane_b32 s9, v255, 31
	s_addc_u32 s15, s9, s15
	s_and_b64 s[22:23], s[2:3], exec
	s_cselect_b32 s9, s15, s21
	s_cselect_b32 s44, s14, s20
	s_add_u32 s18, s18, 0x80080
	s_addc_u32 s19, s19, 0
	s_add_u32 s45, s20, 0x100
	s_addc_u32 s50, s21, 0
	s_mov_b32 s51, -2
	s_add_u32 s20, s18, 0xfff80080
	s_addc_u32 s21, s19, -1
	s_add_i32 s56, 0, 0x10000
	s_cmp_eq_u32 s51, 28
	s_cselect_b32 s23, s11, s21
	s_cselect_b32 s22, s42, s20
	s_cselect_b32 s21, s9, s50
	s_cselect_b32 s20, s44, s45
	s_add_i32 s63, 0, 0x14000
	s_add_i32 m0, s27, 0xc000
	s_nop 0
	global_load_lds_dwordx4 v136, s[18:19]
	s_add_i32 m0, s27, 0xe000
	s_nop 0
	global_load_lds_dwordx4 v138, s[18:19]
	s_waitcnt vmcnt(8)
	s_waitcnt lgkmcnt(0)
	s_setprio 1
	s_barrier
	v_mfma_f32_16x16x32_bf16 v[128:131], v[184:187], v[216:219], 0
	v_mfma_f32_16x16x32_bf16 v[120:123], v[192:195], v[216:219], 0
	v_mfma_f32_16x16x32_bf16 v[112:115], v[184:187], v[224:227], 0
	v_mfma_f32_16x16x32_bf16 v[104:107], v[192:195], v[224:227], 0
	v_mfma_f32_16x16x32_bf16 v[96:99], v[184:187], v[232:235], 0
	v_mfma_f32_16x16x32_bf16 v[88:91], v[192:195], v[232:235], 0
	v_mfma_f32_16x16x32_bf16 v[80:83], v[184:187], v[240:243], 0
	v_mfma_f32_16x16x32_bf16 v[72:75], v[192:195], v[240:243], 0
	v_mfma_f32_16x16x32_bf16 v[128:131], v[188:191], v[220:223], v[128:131]
	v_mfma_f32_16x16x32_bf16 v[120:123], v[196:199], v[220:223], v[120:123]
	v_mfma_f32_16x16x32_bf16 v[112:115], v[188:191], v[228:231], v[112:115]
	v_mfma_f32_16x16x32_bf16 v[104:107], v[196:199], v[228:231], v[104:107]
	v_mfma_f32_16x16x32_bf16 v[96:99], v[188:191], v[236:239], v[96:99]
	v_mfma_f32_16x16x32_bf16 v[88:91], v[196:199], v[236:239], v[88:91]
	v_mfma_f32_16x16x32_bf16 v[80:83], v[188:191], v[244:247], v[80:83]
	v_mfma_f32_16x16x32_bf16 v[72:75], v[196:199], v[244:247], v[72:75]
	v_mfma_f32_16x16x32_bf16 v[124:127], v[200:203], v[216:219], 0
	v_mfma_f32_16x16x32_bf16 v[116:119], v[208:211], v[216:219], 0
	v_mfma_f32_16x16x32_bf16 v[108:111], v[200:203], v[224:227], 0
	v_mfma_f32_16x16x32_bf16 v[100:103], v[208:211], v[224:227], 0
	v_mfma_f32_16x16x32_bf16 v[92:95], v[200:203], v[232:235], 0
	v_mfma_f32_16x16x32_bf16 v[84:87], v[208:211], v[232:235], 0
	v_mfma_f32_16x16x32_bf16 v[76:79], v[200:203], v[240:243], 0
	v_mfma_f32_16x16x32_bf16 v[68:71], v[208:211], v[240:243], 0
	v_mfma_f32_16x16x32_bf16 v[124:127], v[204:207], v[220:223], v[124:127]
	v_mfma_f32_16x16x32_bf16 v[116:119], v[212:215], v[220:223], v[116:119]
	v_mfma_f32_16x16x32_bf16 v[108:111], v[204:207], v[228:231], v[108:111]
	v_mfma_f32_16x16x32_bf16 v[100:103], v[212:215], v[228:231], v[100:103]
	v_mfma_f32_16x16x32_bf16 v[92:95], v[204:207], v[236:239], v[92:95]
	v_mfma_f32_16x16x32_bf16 v[84:87], v[212:215], v[236:239], v[84:87]
	v_mfma_f32_16x16x32_bf16 v[76:79], v[204:207], v[244:247], v[76:79]
	v_mfma_f32_16x16x32_bf16 v[68:71], v[212:215], v[244:247], v[68:71]
	s_barrier
	s_setprio 0
	s_add_i32 s56, s56, s25
	s_mov_b32 m0, s56
	ds_read_b128 v[216:219], v155 offset:16384
	ds_read_b128 v[220:223], v155 offset:17408
	ds_read_b128 v[224:227], v155 offset:18432
	ds_read_b128 v[228:231], v155 offset:19456
	ds_read_b128 v[232:235], v155 offset:20480
	ds_read_b128 v[236:239], v155 offset:21504
	ds_read_b128 v[240:243], v155 offset:22528
	ds_read_b128 v[244:247], v155 offset:23552
	global_load_lds_dwordx4 v2, s[20:21]
	s_add_i32 m0, s56, 0x2000
	s_add_u32 s56, s20, 0x80000
	s_addc_u32 s57, s21, 0
	s_add_i32 s63, s63, s25
	global_load_lds_dwordx4 v0, s[20:21]
	s_mov_b32 m0, s63
	v_lshl_add_u64 v[252:253], s[22:23], 0, v[132:133]
	global_load_lds_dwordx4 v2, s[56:57]
	s_add_i32 m0, s63, 0x2000
	s_nop 0
	global_load_lds_dwordx4 v0, s[56:57]
	v_lshl_add_u64 v[250:251], s[22:23], 0, v[134:135]
	s_mov_b32 m0, s27
	s_nop 0
	global_load_lds_dwordx4 v[250:251], off
	s_mov_b32 m0, s28
	s_nop 0
	global_load_lds_dwordx4 v[252:253], off
	s_waitcnt vmcnt(8)
	s_waitcnt lgkmcnt(0)
	s_setprio 1
	s_barrier
	v_mfma_f32_16x16x32_bf16 v[64:67], v[184:187], v[216:219], 0
	v_mfma_f32_16x16x32_bf16 v[56:59], v[192:195], v[216:219], 0
	v_mfma_f32_16x16x32_bf16 v[48:51], v[184:187], v[224:227], 0
	v_mfma_f32_16x16x32_bf16 v[40:43], v[192:195], v[224:227], 0
	v_mfma_f32_16x16x32_bf16 v[32:35], v[184:187], v[232:235], 0
	v_mfma_f32_16x16x32_bf16 v[24:27], v[192:195], v[232:235], 0
	v_mfma_f32_16x16x32_bf16 v[16:19], v[184:187], v[240:243], 0
	v_mfma_f32_16x16x32_bf16 v[8:11], v[192:195], v[240:243], 0
	v_mfma_f32_16x16x32_bf16 v[64:67], v[188:191], v[220:223], v[64:67]
	v_mfma_f32_16x16x32_bf16 v[56:59], v[196:199], v[220:223], v[56:59]
	v_mfma_f32_16x16x32_bf16 v[48:51], v[188:191], v[228:231], v[48:51]
	v_mfma_f32_16x16x32_bf16 v[40:43], v[196:199], v[228:231], v[40:43]
	v_mfma_f32_16x16x32_bf16 v[32:35], v[188:191], v[236:239], v[32:35]
	v_mfma_f32_16x16x32_bf16 v[24:27], v[196:199], v[236:239], v[24:27]
	v_mfma_f32_16x16x32_bf16 v[16:19], v[188:191], v[244:247], v[16:19]
	v_mfma_f32_16x16x32_bf16 v[8:11], v[196:199], v[244:247], v[8:11]
	v_mfma_f32_16x16x32_bf16 v[60:63], v[200:203], v[216:219], 0
	v_mfma_f32_16x16x32_bf16 v[52:55], v[208:211], v[216:219], 0
	v_mfma_f32_16x16x32_bf16 v[44:47], v[200:203], v[224:227], 0
	v_mfma_f32_16x16x32_bf16 v[36:39], v[208:211], v[224:227], 0
	v_mfma_f32_16x16x32_bf16 v[28:31], v[200:203], v[232:235], 0
	v_mfma_f32_16x16x32_bf16 v[20:23], v[208:211], v[232:235], 0
	v_mfma_f32_16x16x32_bf16 v[12:15], v[200:203], v[240:243], 0
	v_mfma_f32_16x16x32_bf16 v[4:7], v[208:211], v[240:243], 0
	v_mfma_f32_16x16x32_bf16 v[60:63], v[204:207], v[220:223], v[60:63]
	v_mfma_f32_16x16x32_bf16 v[52:55], v[212:215], v[220:223], v[52:55]
	v_mfma_f32_16x16x32_bf16 v[44:47], v[204:207], v[228:231], v[44:47]
	v_mfma_f32_16x16x32_bf16 v[36:39], v[212:215], v[228:231], v[36:39]
	v_mfma_f32_16x16x32_bf16 v[28:31], v[204:207], v[236:239], v[28:31]
	v_mfma_f32_16x16x32_bf16 v[20:23], v[212:215], v[236:239], v[20:23]
	v_mfma_f32_16x16x32_bf16 v[12:15], v[204:207], v[244:247], v[12:15]
	v_mfma_f32_16x16x32_bf16 v[4:7], v[212:215], v[244:247], v[4:7]
	s_barrier
; #define PG8_STAGE(bufoff, gbase, voff) do { _Pragma("unroll") for (int _i = 0; _i < 2; ++_i) \
;         __builtin_amdgcn_global_load_lds((const unsigned*)((const char*)(gbase) + (voff)[_i]), (PG8_LAS unsigned*)(lds + (bufoff) + ldsw + _i * 8192), 16, 0, 0); } while (0)
; #define PG8_LDA(dst, b, h) do { _Pragma("unroll") for (int m = 0; m < 4; ++m) _Pragma("unroll") for (int k = 0; k < 2; ++k) dst[m][k] = *(const PG8_LAS bf16x8*)(lds + PG8_SA(b, h) + aoff + m * 2048 + k * 1024); } while (0)
; #define PG8_LDB(dst, b, h) do { _Pragma("unroll") for (int n = 0; n < 2; ++n) _Pragma("unroll") for (int k = 0; k < 2; ++k) dst[n][k] = *(const PG8_LAS bf16x8*)(lds + PG8_SB(b, h) + boff + n * 2048 + k * 1024); } while (0)
; #define PG8_MMA(ai, bj, At, Bt) do { __builtin_amdgcn_s_setprio(1); _Pragma("unroll") for (int m = 0; m < 4; ++m) _Pragma("unroll") for (int n = 0; n < 2; ++n) _Pragma("unroll") for (int k = 0; k < 2; ++k) \
;         acc[ai][bj][m][n] = __builtin_amdgcn_mfma_f32_16x16x32_bf16(Bt[n][k], At[m][k], acc[ai][bj][m][n], 0, 0, 0); __builtin_amdgcn_s_setprio(0); } while (0)
; #define PG8_WAIT_V(n) asm volatile("s_waitcnt vmcnt(" #n ")" ::: "memory")
; #define PG8_WAIT_L(n) asm volatile("s_waitcnt lgkmcnt(" #n ")" ::: "memory")
; #define PG8_BAR __builtin_amdgcn_s_barrier()
; #define PG8_SCHED __builtin_amdgcn_sched_barrier(0)
; template <class Epi, class Sched, bool ALIGN_EPI = false, bool SP2 = false>
; __device__ __forceinline__ void gemm_phase(PG8_LAS unsigned char* lds, const Gemm g, const Sched& S, const Epi& E) {
;     ...
;             PG8_LDB(B0, 1, 0); PG8_LDB(B1, 1, 1); PG8_SCHED; PG8_LDA(At, 1, 0); PG8_STAGE(PG8_SA(0, 1), a2 + hstep, voffA);
;             PG8_WAIT_V(8); PG8_WAIT_L(0); PG8_BAR; PG8_MMA(0, 0, At, B0); PG8_MMA(0, 1, At, B1); PG8_BAR; PG8_SCHED;
;             PG8_LDA(At, 1, 1); PG8_STAGE(PG8_SB(1, 0), b3, voffB); PG8_STAGE(PG8_SB(1, 1), b3 + hstep, voffB); PG8_STAGE(PG8_SA(1, 0), a3, voffA);
;             PG8_WAIT_V(8); PG8_WAIT_L(0); PG8_BAR; PG8_MMA(1, 0, At, B0); PG8_MMA(1, 1, At, B1); PG8_BAR; PG8_SCHED;
	s_setprio 0
	s_add_i32 s56, 0, 0x18000
	v_add_u32_e32 v161, s56, v153
	s_add_i32 s57, 0, 0x1c000
	ds_read_b128 v[184:187], v161
	ds_read_b128 v[188:191], v161 offset:1024
	ds_read_b128 v[192:195], v161 offset:2048
	ds_read_b128 v[196:199], v161 offset:3072
	v_add_u32_e32 v161, s57, v153
	ds_read_b128 v[200:203], v161
	ds_read_b128 v[204:207], v161 offset:1024
	ds_read_b128 v[208:211], v161 offset:2048
	ds_read_b128 v[212:215], v161 offset:3072
	s_add_u32 s22, s22, 0x80000
	s_addc_u32 s23, s23, 0
	s_mov_b32 m0, s29
	ds_read_b128 v[216:219], v155 offset:32768
	ds_read_b128 v[220:223], v155 offset:33792
	ds_read_b128 v[224:227], v155 offset:34816
	ds_read_b128 v[228:231], v155 offset:35840
	ds_read_b128 v[232:235], v155 offset:36864
	ds_read_b128 v[236:239], v155 offset:37888
	ds_read_b128 v[240:243], v155 offset:38912
	ds_read_b128 v[244:247], v155 offset:39936
	global_load_lds_dwordx4 v134, s[22:23]
	s_mov_b32 m0, s30
	s_nop 0
	global_load_lds_dwordx4 v132, s[22:23]
	s_waitcnt vmcnt(8)
	s_waitcnt lgkmcnt(0)
	s_setprio 1
	s_barrier
	v_mfma_f32_16x16x32_bf16 v[128:131], v[184:187], v[216:219], v[128:131]
	v_mfma_f32_16x16x32_bf16 v[120:123], v[192:195], v[216:219], v[120:123]
	v_mfma_f32_16x16x32_bf16 v[112:115], v[184:187], v[224:227], v[112:115]
	v_mfma_f32_16x16x32_bf16 v[104:107], v[192:195], v[224:227], v[104:107]
	v_mfma_f32_16x16x32_bf16 v[96:99], v[184:187], v[232:235], v[96:99]
	v_mfma_f32_16x16x32_bf16 v[88:91], v[192:195], v[232:235], v[88:91]
	v_mfma_f32_16x16x32_bf16 v[80:83], v[184:187], v[240:243], v[80:83]
	v_mfma_f32_16x16x32_bf16 v[72:75], v[192:195], v[240:243], v[72:75]
	v_mfma_f32_16x16x32_bf16 v[128:131], v[188:191], v[220:223], v[128:131]
	v_mfma_f32_16x16x32_bf16 v[120:123], v[196:199], v[220:223], v[120:123]
	v_mfma_f32_16x16x32_bf16 v[112:115], v[188:191], v[228:231], v[112:115]
	v_mfma_f32_16x16x32_bf16 v[104:107], v[196:199], v[228:231], v[104:107]
	v_mfma_f32_16x16x32_bf16 v[96:99], v[188:191], v[236:239], v[96:99]
	v_mfma_f32_16x16x32_bf16 v[88:91], v[196:199], v[236:239], v[88:91]
	v_mfma_f32_16x16x32_bf16 v[80:83], v[188:191], v[244:247], v[80:83]
	v_mfma_f32_16x16x32_bf16 v[72:75], v[196:199], v[244:247], v[72:75]
	v_mfma_f32_16x16x32_bf16 v[124:127], v[200:203], v[216:219], v[124:127]
	v_mfma_f32_16x16x32_bf16 v[116:119], v[208:211], v[216:219], v[116:119]
	v_mfma_f32_16x16x32_bf16 v[108:111], v[200:203], v[224:227], v[108:111]
	v_mfma_f32_16x16x32_bf16 v[100:103], v[208:211], v[224:227], v[100:103]
	v_mfma_f32_16x16x32_bf16 v[92:95], v[200:203], v[232:235], v[92:95]
	v_mfma_f32_16x16x32_bf16 v[84:87], v[208:211], v[232:235], v[84:87]
	v_mfma_f32_16x16x32_bf16 v[76:79], v[200:203], v[240:243], v[76:79]
	v_mfma_f32_16x16x32_bf16 v[68:71], v[208:211], v[240:243], v[68:71]
	v_mfma_f32_16x16x32_bf16 v[124:127], v[204:207], v[220:223], v[124:127]
	v_mfma_f32_16x16x32_bf16 v[116:119], v[212:215], v[220:223], v[116:119]
	v_mfma_f32_16x16x32_bf16 v[108:111], v[204:207], v[228:231], v[108:111]
	v_mfma_f32_16x16x32_bf16 v[100:103], v[212:215], v[228:231], v[100:103]
	v_mfma_f32_16x16x32_bf16 v[92:95], v[204:207], v[236:239], v[92:95]
	v_mfma_f32_16x16x32_bf16 v[84:87], v[212:215], v[236:239], v[84:87]
	v_mfma_f32_16x16x32_bf16 v[76:79], v[204:207], v[244:247], v[76:79]
	v_mfma_f32_16x16x32_bf16 v[68:71], v[212:215], v[244:247], v[68:71]
	s_barrier
	s_setprio 0
	s_add_i32 s22, s56, s25
	s_mov_b32 m0, s22
	ds_read_b128 v[216:219], v155 offset:49152
	ds_read_b128 v[220:223], v155 offset:50176
	ds_read_b128 v[224:227], v155 offset:51200
	ds_read_b128 v[228:231], v155 offset:52224
	ds_read_b128 v[232:235], v155 offset:53248
	ds_read_b128 v[236:239], v155 offset:54272
	ds_read_b128 v[240:243], v155 offset:55296
	ds_read_b128 v[244:247], v155 offset:56320
	s_add_u32 vcc_lo, s20, 0x80
	s_addc_u32 vcc_hi, s21, 0
	global_load_lds_dwordx4 v2, vcc
	s_add_i32 m0, s22, 0x2000
	s_add_u32 s20, s20, 0x80080
	s_addc_u32 s21, s21, 0
	s_add_i32 s22, s57, s25
	s_add_u32 vcc_lo, s20, 0xfff80000
	s_addc_u32 vcc_hi, s21, -1
	global_load_lds_dwordx4 v0, vcc
	s_mov_b32 m0, s22
	s_nop 0
	global_load_lds_dwordx4 v2, s[20:21]
	s_add_i32 m0, s22, 0x2000
	s_nop 0
	global_load_lds_dwordx4 v0, s[20:21]
	v_lshl_add_u64 v[150:151], v[250:251], 0, s[36:37]
	s_mov_b32 m0, s31
	s_nop 0
	global_load_lds_dwordx4 v[150:151], off
	v_lshl_add_u64 v[150:151], v[252:253], 0, s[36:37]
	s_mov_b32 m0, s34
	s_nop 0
	global_load_lds_dwordx4 v[150:151], off
	s_waitcnt vmcnt(8)
	s_waitcnt lgkmcnt(0)
	s_setprio 1
	s_barrier
	v_mfma_f32_16x16x32_bf16 v[64:67], v[184:187], v[216:219], v[64:67]
	v_mfma_f32_16x16x32_bf16 v[56:59], v[192:195], v[216:219], v[56:59]
	v_mfma_f32_16x16x32_bf16 v[48:51], v[184:187], v[224:227], v[48:51]
	v_mfma_f32_16x16x32_bf16 v[40:43], v[192:195], v[224:227], v[40:43]
	v_mfma_f32_16x16x32_bf16 v[32:35], v[184:187], v[232:235], v[32:35]
	v_mfma_f32_16x16x32_bf16 v[24:27], v[192:195], v[232:235], v[24:27]
	v_mfma_f32_16x16x32_bf16 v[16:19], v[184:187], v[240:243], v[16:19]
	v_mfma_f32_16x16x32_bf16 v[8:11], v[192:195], v[240:243], v[8:11]
	v_mfma_f32_16x16x32_bf16 v[64:67], v[188:191], v[220:223], v[64:67]
	v_mfma_f32_16x16x32_bf16 v[56:59], v[196:199], v[220:223], v[56:59]
	v_mfma_f32_16x16x32_bf16 v[48:51], v[188:191], v[228:231], v[48:51]
	v_mfma_f32_16x16x32_bf16 v[40:43], v[196:199], v[228:231], v[40:43]
	v_mfma_f32_16x16x32_bf16 v[32:35], v[188:191], v[236:239], v[32:35]
	v_mfma_f32_16x16x32_bf16 v[24:27], v[196:199], v[236:239], v[24:27]
	v_mfma_f32_16x16x32_bf16 v[16:19], v[188:191], v[244:247], v[16:19]
	v_mfma_f32_16x16x32_bf16 v[8:11], v[196:199], v[244:247], v[8:11]
	v_mfma_f32_16x16x32_bf16 v[60:63], v[200:203], v[216:219], v[60:63]
	v_mfma_f32_16x16x32_bf16 v[52:55], v[208:211], v[216:219], v[52:55]
	v_mfma_f32_16x16x32_bf16 v[44:47], v[200:203], v[224:227], v[44:47]
	v_mfma_f32_16x16x32_bf16 v[36:39], v[208:211], v[224:227], v[36:39]
	v_mfma_f32_16x16x32_bf16 v[28:31], v[200:203], v[232:235], v[28:31]
	v_mfma_f32_16x16x32_bf16 v[20:23], v[208:211], v[232:235], v[20:23]
	v_mfma_f32_16x16x32_bf16 v[12:15], v[200:203], v[240:243], v[12:15]
	v_mfma_f32_16x16x32_bf16 v[4:7], v[208:211], v[240:243], v[4:7]
	v_mfma_f32_16x16x32_bf16 v[60:63], v[204:207], v[220:223], v[60:63]
	v_mfma_f32_16x16x32_bf16 v[52:55], v[212:215], v[220:223], v[52:55]
	v_mfma_f32_16x16x32_bf16 v[44:47], v[204:207], v[228:231], v[44:47]
	v_mfma_f32_16x16x32_bf16 v[36:39], v[212:215], v[228:231], v[36:39]
	v_mfma_f32_16x16x32_bf16 v[28:31], v[204:207], v[236:239], v[28:31]
	v_mfma_f32_16x16x32_bf16 v[20:23], v[212:215], v[236:239], v[20:23]
	v_mfma_f32_16x16x32_bf16 v[12:15], v[204:207], v[244:247], v[12:15]
	v_mfma_f32_16x16x32_bf16 v[4:7], v[212:215], v[244:247], v[4:7]
	s_barrier
	s_setprio 0
	s_add_i32 s51, s51, 2
	s_add_u32 s18, s18, 0x100
	s_addc_u32 s19, s19, 0
	s_add_u32 s45, s45, 0x100
	s_addc_u32 s50, s50, 0
	s_cmp_gt_u32 s51, 29

; __device__ __forceinline__ unsigned cvt_pk_bf16(float lo, float hi) { unsigned r; asm volatile("v_cvt_pk_bf16_f32 %0, %1, %2" : "=v"(r) : "v"(lo), "v"(hi)); return r; }
; #define PG8_STAGE(bufoff, gbase, voff) do { _Pragma("unroll") for (int _i = 0; _i < 2; ++_i) \
;         __builtin_amdgcn_global_load_lds((const unsigned*)((const char*)(gbase) + (voff)[_i]), (PG8_LAS unsigned*)(lds + (bufoff) + ldsw + _i * 8192), 16, 0, 0); } while (0)
; #define PG8_LDA(dst, b, h) do { _Pragma("unroll") for (int m = 0; m < 4; ++m) _Pragma("unroll") for (int k = 0; k < 2; ++k) dst[m][k] = *(const PG8_LAS bf16x8*)(lds + PG8_SA(b, h) + aoff + m * 2048 + k * 1024); } while (0)
; #define PG8_LDB(dst, b, h) do { _Pragma("unroll") for (int n = 0; n < 2; ++n) _Pragma("unroll") for (int k = 0; k < 2; ++k) dst[n][k] = *(const PG8_LAS bf16x8*)(lds + PG8_SB(b, h) + boff + n * 2048 + k * 1024); } while (0)
; #define PG8_SCHED __builtin_amdgcn_sched_barrier(0)
;     __device__ __forceinline__ void operator()(const f32x4 (&acc)[2][2][4][2], const Unit& u, int wr, int wc, int fr, int fq, const float (&pf)[8]) const {
;         const int row0 = u.pm * BM + wr * 64 + fr, col0 = u.pn * HALF + wc * 32 + 8 * fq;
; #pragma unroll
;         for (int ai = 0; ai < 2; ++ai)
; #pragma unroll
;             for (int m = 0; m < 4; ++m) { const int row = row0 + ai * HALF + m * 16;
;                 const float c = (float)__float_as_uint(pf[ai * 4 + m]) * (INV_D / SSQ_SCALE) + RMS_EPS_C, k1 = __builtin_amdgcn_rsqf(c) * -1.4426950408889634f;
;                 float o[8];
; #pragma unroll
;                 for (int e = 0; e < 8; ++e) { const float a = acc[ai][0][m][e >> 2][e & 3], b = acc[ai][1][m][e >> 2][e & 3];
;                     o[e] = (a * b) * __builtin_amdgcn_rcpf(__builtin_fmaf(__builtin_amdgcn_exp2f(a * k1), c, c)); }
;                 u32x4 w; w.x = cvt_pk_bf16(o[0], o[1]); w.y = cvt_pk_bf16(o[2], o[3]); w.z = cvt_pk_bf16(o[4], o[5]); w.w = cvt_pk_bf16(o[6], o[7]);
;                 *(u32x4*)(H + (size_t)row * ldh + col0) = w; }
; template <class Epi, class Sched, bool ALIGN_EPI = false, bool SP2 = false>
; __device__ __forceinline__ void gemm_phase(PG8_LAS unsigned char* lds, const Gemm g, const Sched& S, const Epi& E) {
;     ...
;             PG8_LDB(B0, 0, 0); PG8_LDB(B1, 0, 1); PG8_SCHED; PG8_LDA(At, 0, 0); PG8_STAGE(PG8_SA(1, 1), a1 + hstep, voffA);
.LBB0_88:
	v_add_u32_e32 v166, 0x10000, v153
	ds_read_b128 v[184:187], v166
	ds_read_b128 v[188:191], v166 offset:1024
	ds_read_b128 v[192:195], v166 offset:2048
	ds_read_b128 v[196:199], v166 offset:3072
	v_add_u32_e32 v167, 0x14000, v153
	ds_read_b128 v[200:203], v167
	ds_read_b128 v[204:207], v167 offset:1024
	ds_read_b128 v[208:211], v167 offset:2048
	ds_read_b128 v[212:215], v167 offset:3072
	ds_read_b128 v[216:219], v155
	ds_read_b128 v[220:223], v155 offset:1024
	ds_read_b128 v[224:227], v155 offset:2048
	ds_read_b128 v[228:231], v155 offset:3072
	ds_read_b128 v[232:235], v155 offset:4096
	ds_read_b128 v[236:239], v155 offset:5120
	ds_read_b128 v[240:243], v155 offset:6144
	ds_read_b128 v[244:247], v155 offset:7168
	s_waitcnt vmcnt(0)
	v_cvt_f32_u32_e32 v164, v164
	v_mul_f32_e32 v124, v128, v124
	v_mul_f32_e32 v116, v120, v116
	v_mul_f32_e32 v125, v129, v125
	v_fmamk_f32 v164, v164, 0x34800000, v141
	v_rsq_f32_e32 v165, v164
	v_mul_f32_e32 v117, v121, v117
	v_mul_f32_e32 v126, v130, v126
	v_mul_f32_e32 v118, v122, v118
	v_mul_f32_e32 v165, 0xbfb8aa3b, v165
	v_mul_f32_e32 v128, v165, v128
	v_mul_f32_e32 v120, v165, v120
	v_exp_f32_e32 v128, v128
	v_exp_f32_e32 v120, v120
	v_lshl_or_b32 v150, s17, 7, v154
	v_mul_f32_e32 v127, v131, v127
	v_fma_f32 v128, v128, v164, v164
	v_fma_f32 v120, v120, v164, v164
	v_rcp_f32_e32 v128, v128
	v_rcp_f32_e32 v120, v120
	v_mul_f32_e32 v119, v123, v119
	v_lshl_add_u32 v161, s16, 8, v152
	v_mul_f32_e32 v124, v128, v124
	v_mul_f32_e32 v128, v165, v129
	v_mul_f32_e32 v116, v120, v116
	v_mul_f32_e32 v120, v165, v121
	v_exp_f32_e32 v128, v128
	v_exp_f32_e32 v120, v120
	v_ashrrev_i32_e32 v151, 31, v150
	v_mul_f32_e32 v108, v112, v108
	v_fma_f32 v128, v128, v164, v164
	v_fma_f32 v120, v120, v164, v164
	v_rcp_f32_e32 v128, v128
	v_rcp_f32_e32 v120, v120
	v_mul_f32_e32 v100, v104, v100
	v_mul_f32_e32 v109, v113, v109
	v_mul_f32_e32 v125, v128, v125
	v_mul_f32_e32 v128, v165, v130
	v_mul_f32_e32 v117, v120, v117
	v_mul_f32_e32 v120, v165, v122
	v_exp_f32_e32 v128, v128
	v_exp_f32_e32 v120, v120
	v_mul_f32_e32 v110, v114, v110
	v_mul_f32_e32 v111, v115, v111
	v_fma_f32 v128, v128, v164, v164
	v_fma_f32 v120, v120, v164, v164
	v_rcp_f32_e32 v128, v128
	v_rcp_f32_e32 v120, v120
	v_mul_f32_e32 v92, v96, v92
	v_mul_f32_e32 v84, v88, v84
	v_mul_f32_e32 v126, v128, v126
	v_mul_f32_e32 v128, v165, v131
	v_mul_f32_e32 v118, v120, v118
	v_mul_f32_e32 v120, v165, v123
	v_exp_f32_e32 v128, v128
	v_exp_f32_e32 v120, v120
	v_mul_f32_e32 v93, v97, v93
	v_mul_f32_e32 v94, v98, v94
	v_fma_f32 v128, v128, v164, v164
	v_fmac_f32_e32 v164, v120, v164
	v_rcp_f32_e32 v128, v128
	v_rcp_f32_e32 v120, v164
	v_mul_f32_e32 v95, v99, v95
	v_mul_f32_e32 v76, v80, v76
	v_mul_f32_e32 v127, v128, v127
	v_mul_f32_e32 v119, v120, v119
	v_cvt_pk_bf16_f32 v120, v124, v125
	v_cvt_pk_bf16_f32 v121, v126, v127
	v_cvt_pk_bf16_f32 v122, v116, v117
	v_mov_b64_e32 v[116:117], s[48:49]
	v_cvt_pk_bf16_f32 v123, v118, v119
	v_mad_i64_i32 v[124:125], s[16:17], v161, s58, v[116:117]
	v_lshlrev_b64 v[118:119], 1, v[150:151]
	v_lshl_add_u64 v[124:125], v[124:125], 0, v[118:119]
	global_store_dwordx4 v[124:125], v[120:123], off
	v_mul_f32_e32 v68, v72, v68
	v_mul_f32_e32 v77, v81, v77
	v_cvt_f32_u32_e32 v120, v163
	v_mul_f32_e32 v78, v82, v78
	v_mul_f32_e32 v79, v83, v79
	v_mul_f32_e32 v60, v64, v60
	v_fmamk_f32 v120, v120, 0x34800000, v141
	v_rsq_f32_e32 v121, v120
	v_mul_f32_e32 v52, v56, v52
	v_mul_f32_e32 v61, v65, v61
	v_mul_f32_e32 v62, v66, v62
	v_mul_f32_e32 v121, 0xbfb8aa3b, v121
	v_mul_f32_e32 v112, v121, v112
	v_mul_f32_e32 v104, v121, v104
	v_exp_f32_e32 v112, v112
	v_exp_f32_e32 v104, v104
	v_mul_f32_e32 v63, v67, v63
	v_mul_f32_e32 v44, v48, v44
	v_fma_f32 v112, v112, v120, v120
	v_fma_f32 v104, v104, v120, v120
	v_rcp_f32_e32 v112, v112
	v_rcp_f32_e32 v104, v104
	v_mul_f32_e32 v36, v40, v36
	v_mul_f32_e32 v45, v49, v45
	v_mul_f32_e32 v108, v112, v108
	v_mul_f32_e32 v112, v121, v113
	v_mul_f32_e32 v104, v104, v100
	v_mul_f32_e32 v100, v105, v101
	v_mul_f32_e32 v101, v121, v105
	v_exp_f32_e32 v112, v112
	v_exp_f32_e32 v101, v101
	v_mul_f32_e32 v46, v50, v46
	v_mul_f32_e32 v47, v51, v47
	v_fma_f32 v112, v112, v120, v120
	v_fma_f32 v101, v101, v120, v120
	v_rcp_f32_e32 v112, v112
	v_rcp_f32_e32 v101, v101
	v_mul_f32_e32 v28, v32, v28
	v_mul_f32_e32 v20, v24, v20
	v_mul_f32_e32 v109, v112, v109
	v_mul_f32_e32 v112, v121, v114
	v_mul_f32_e32 v105, v101, v100
	v_mul_f32_e32 v101, v121, v106
	v_exp_f32_e32 v112, v112
	v_exp_f32_e32 v101, v101
	v_mul_f32_e32 v100, v106, v102
	v_mul_f32_e32 v29, v33, v29
	v_fma_f32 v112, v112, v120, v120
	v_fma_f32 v101, v101, v120, v120
	v_rcp_f32_e32 v112, v112
	v_rcp_f32_e32 v101, v101
	v_mul_f32_e32 v30, v34, v30
	v_mul_f32_e32 v31, v35, v31
	v_mul_f32_e32 v110, v112, v110
	v_mul_f32_e32 v112, v121, v115
	v_mul_f32_e32 v106, v101, v100
	v_mul_f32_e32 v101, v121, v107
	v_exp_f32_e32 v112, v112
	v_exp_f32_e32 v101, v101
	v_mul_f32_e32 v100, v107, v103
	v_or_b32_e32 v107, 16, v161
	v_fma_f32 v112, v112, v120, v120
	v_fmac_f32_e32 v120, v101, v120
	v_rcp_f32_e32 v112, v112
	v_rcp_f32_e32 v101, v120
	v_mul_f32_e32 v12, v16, v12
	v_mul_f32_e32 v4, v8, v4
	v_mul_f32_e32 v111, v112, v111
	v_mul_f32_e32 v103, v101, v100
	v_cvt_pk_bf16_f32 v100, v108, v109
	v_cvt_pk_bf16_f32 v101, v110, v111
	v_cvt_pk_bf16_f32 v102, v104, v105
	v_mad_i64_i32 v[104:105], s[16:17], v107, s58, v[116:117]
	v_lshl_add_u64 v[104:105], v[104:105], 0, v[118:119]
	v_cvt_pk_bf16_f32 v103, v106, v103
	global_store_dwordx4 v[104:105], v[100:103], off
	v_mul_f32_e32 v13, v17, v13
	v_mul_f32_e32 v14, v18, v14
	v_cvt_f32_u32_e32 v100, v162
	v_mul_f32_e32 v15, v19, v15
; __device__ __forceinline__ unsigned cvt_pk_bf16(float lo, float hi) { unsigned r; asm volatile("v_cvt_pk_bf16_f32 %0, %1, %2" : "=v"(r) : "v"(lo), "v"(hi)); return r; }
;     __device__ __forceinline__ void operator()(const f32x4 (&acc)[2][2][4][2], const Unit& u, int wr, int wc, int fr, int fq, const float (&pf)[8]) const {
;         const int row0 = u.pm * BM + wr * 64 + fr, col0 = u.pn * HALF + wc * 32 + 8 * fq;
; #pragma unroll
;         for (int ai = 0; ai < 2; ++ai)
; #pragma unroll
;             for (int m = 0; m < 4; ++m) { const int row = row0 + ai * HALF + m * 16;
;                 const float c = (float)__float_as_uint(pf[ai * 4 + m]) * (INV_D / SSQ_SCALE) + RMS_EPS_C, k1 = __builtin_amdgcn_rsqf(c) * -1.4426950408889634f;
;                 float o[8];
; #pragma unroll
;                 for (int e = 0; e < 8; ++e) { const float a = acc[ai][0][m][e >> 2][e & 3], b = acc[ai][1][m][e >> 2][e & 3];
;                     o[e] = (a * b) * __builtin_amdgcn_rcpf(__builtin_fmaf(__builtin_amdgcn_exp2f(a * k1), c, c)); }
;                 u32x4 w; w.x = cvt_pk_bf16(o[0], o[1]); w.y = cvt_pk_bf16(o[2], o[3]); w.z = cvt_pk_bf16(o[4], o[5]); w.w = cvt_pk_bf16(o[6], o[7]);
;                 *(u32x4*)(H + (size_t)row * ldh + col0) = w; }
	s_andn2_b64 vcc, exec, s[2:3]
	v_fmamk_f32 v100, v100, 0x34800000, v141
	v_rsq_f32_e32 v101, v100
	s_nop 0
	v_mul_f32_e32 v101, 0xbfb8aa3b, v101
	v_mul_f32_e32 v96, v101, v96
	v_mul_f32_e32 v88, v101, v88
	v_exp_f32_e32 v96, v96
	v_exp_f32_e32 v88, v88
	v_fma_f32 v96, v96, v100, v100
	v_fma_f32 v88, v88, v100, v100
	v_rcp_f32_e32 v96, v96
	v_rcp_f32_e32 v88, v88
	v_mul_f32_e32 v92, v96, v92
	v_mul_f32_e32 v96, v101, v97
	v_mul_f32_e32 v88, v88, v84
	v_mul_f32_e32 v84, v89, v85
	v_mul_f32_e32 v85, v101, v89
	v_exp_f32_e32 v96, v96
	v_exp_f32_e32 v85, v85
	v_fma_f32 v96, v96, v100, v100
	v_fma_f32 v85, v85, v100, v100
	v_rcp_f32_e32 v96, v96
	v_rcp_f32_e32 v85, v85
	v_mul_f32_e32 v93, v96, v93
	v_mul_f32_e32 v96, v101, v98
	v_mul_f32_e32 v89, v85, v84
	v_mul_f32_e32 v85, v101, v90
	v_exp_f32_e32 v96, v96
	v_exp_f32_e32 v85, v85
	v_mul_f32_e32 v84, v90, v86
	v_fma_f32 v96, v96, v100, v100
	v_fma_f32 v85, v85, v100, v100
	v_rcp_f32_e32 v96, v96
	v_rcp_f32_e32 v85, v85
	v_mul_f32_e32 v94, v96, v94
	v_mul_f32_e32 v96, v101, v99
	v_mul_f32_e32 v90, v85, v84
	v_mul_f32_e32 v85, v101, v91
	v_exp_f32_e32 v96, v96
	v_exp_f32_e32 v85, v85
	v_mul_f32_e32 v84, v91, v87
	v_or_b32_e32 v91, 32, v161
	v_fma_f32 v96, v96, v100, v100
	v_fmac_f32_e32 v100, v85, v100
	v_rcp_f32_e32 v96, v96
	v_rcp_f32_e32 v85, v100
	v_mul_f32_e32 v95, v96, v95
	v_mul_f32_e32 v87, v85, v84
	v_cvt_pk_bf16_f32 v84, v92, v93
	v_cvt_pk_bf16_f32 v85, v94, v95
	v_cvt_pk_bf16_f32 v86, v88, v89
	v_mad_i64_i32 v[88:89], s[16:17], v91, s58, v[116:117]
	v_lshl_add_u64 v[88:89], v[88:89], 0, v[118:119]
	v_cvt_pk_bf16_f32 v87, v90, v87
	global_store_dwordx4 v[88:89], v[84:87], off
	s_nop 1
	v_cvt_f32_u32_e32 v84, v160
	v_fmamk_f32 v84, v84, 0x34800000, v141
	v_rsq_f32_e32 v85, v84
	s_nop 0
	v_mul_f32_e32 v85, 0xbfb8aa3b, v85
	v_mul_f32_e32 v80, v85, v80
	v_mul_f32_e32 v72, v85, v72
	v_exp_f32_e32 v80, v80
	v_exp_f32_e32 v72, v72
	v_fma_f32 v80, v80, v84, v84
	v_fma_f32 v72, v72, v84, v84
	v_rcp_f32_e32 v80, v80
	v_rcp_f32_e32 v72, v72
	v_mul_f32_e32 v76, v80, v76
	v_mul_f32_e32 v80, v85, v81
	v_mul_f32_e32 v72, v72, v68
	v_mul_f32_e32 v68, v73, v69
	v_mul_f32_e32 v69, v85, v73
	v_exp_f32_e32 v80, v80
	v_exp_f32_e32 v69, v69
	v_fma_f32 v80, v80, v84, v84
	v_fma_f32 v69, v69, v84, v84
	v_rcp_f32_e32 v80, v80
	v_rcp_f32_e32 v69, v69
	v_mul_f32_e32 v77, v80, v77
	v_mul_f32_e32 v80, v85, v82
	v_mul_f32_e32 v73, v69, v68
	v_mul_f32_e32 v69, v85, v74
	v_exp_f32_e32 v80, v80
	v_exp_f32_e32 v69, v69
	v_mul_f32_e32 v68, v74, v70
	v_fma_f32 v80, v80, v84, v84
	v_fma_f32 v69, v69, v84, v84
	v_rcp_f32_e32 v80, v80
	v_rcp_f32_e32 v69, v69
	v_mul_f32_e32 v78, v80, v78
	v_mul_f32_e32 v80, v85, v83
	v_mul_f32_e32 v74, v69, v68
	v_mul_f32_e32 v69, v85, v75
	v_exp_f32_e32 v80, v80
	v_exp_f32_e32 v69, v69
	v_mul_f32_e32 v68, v75, v71
	v_or_b32_e32 v75, 48, v161
	v_fma_f32 v80, v80, v84, v84
	v_fmac_f32_e32 v84, v69, v84
	v_rcp_f32_e32 v80, v80
	v_rcp_f32_e32 v69, v84
	v_mul_f32_e32 v79, v80, v79
	v_mul_f32_e32 v71, v69, v68
	v_cvt_pk_bf16_f32 v68, v76, v77
	v_cvt_pk_bf16_f32 v69, v78, v79
	v_cvt_pk_bf16_f32 v70, v72, v73
	v_mad_i64_i32 v[72:73], s[16:17], v75, s58, v[116:117]
	v_lshl_add_u64 v[72:73], v[72:73], 0, v[118:119]
	v_cvt_pk_bf16_f32 v71, v74, v71
	global_store_dwordx4 v[72:73], v[68:71], off
	s_nop 1
	v_cvt_f32_u32_e32 v69, v159
	v_add_u32_e32 v68, 0x80, v161
	v_fmamk_f32 v69, v69, 0x34800000, v141
	v_rsq_f32_e32 v70, v69
	s_nop 0
	v_mul_f32_e32 v70, 0xbfb8aa3b, v70
	v_mul_f32_e32 v64, v70, v64
	v_mul_f32_e32 v56, v70, v56
	v_exp_f32_e32 v64, v64
	v_exp_f32_e32 v56, v56
	v_fma_f32 v64, v64, v69, v69
	v_fma_f32 v56, v56, v69, v69
	v_rcp_f32_e32 v64, v64
	v_rcp_f32_e32 v56, v56
	v_mul_f32_e32 v60, v64, v60
	v_mul_f32_e32 v64, v70, v65
	v_mul_f32_e32 v56, v56, v52
	v_mul_f32_e32 v52, v57, v53
	v_mul_f32_e32 v53, v70, v57
	v_exp_f32_e32 v64, v64
	v_exp_f32_e32 v53, v53
	v_fma_f32 v64, v64, v69, v69
	v_fma_f32 v53, v53, v69, v69
	v_rcp_f32_e32 v64, v64
	v_rcp_f32_e32 v53, v53
	v_mul_f32_e32 v61, v64, v61
	v_mul_f32_e32 v64, v70, v66
	v_mul_f32_e32 v57, v53, v52
	v_mul_f32_e32 v53, v70, v58
	v_exp_f32_e32 v64, v64
	v_exp_f32_e32 v53, v53
	v_mul_f32_e32 v52, v58, v54
	v_fma_f32 v64, v64, v69, v69
	v_fma_f32 v53, v53, v69, v69
	v_rcp_f32_e32 v64, v64
	v_rcp_f32_e32 v53, v53
	v_mul_f32_e32 v62, v64, v62
	v_mul_f32_e32 v64, v70, v67
	v_mul_f32_e32 v58, v53, v52
	v_mul_f32_e32 v53, v70, v59
	v_exp_f32_e32 v64, v64
	v_exp_f32_e32 v53, v53
	v_mul_f32_e32 v52, v59, v55
	v_fma_f32 v64, v64, v69, v69
	v_fmac_f32_e32 v69, v53, v69
	v_rcp_f32_e32 v64, v64
	v_rcp_f32_e32 v53, v69
	v_mul_f32_e32 v63, v64, v63
	v_mul_f32_e32 v55, v53, v52
	v_cvt_pk_bf16_f32 v52, v60, v61
	v_cvt_pk_bf16_f32 v53, v62, v63
	v_cvt_pk_bf16_f32 v54, v56, v57
	v_mad_i64_i32 v[56:57], s[16:17], v68, s58, v[116:117]
	v_lshl_add_u64 v[56:57], v[56:57], 0, v[118:119]
	v_cvt_pk_bf16_f32 v55, v58, v55
	global_store_dwordx4 v[56:57], v[52:55], off
	s_nop 1
	v_cvt_f32_u32_e32 v52, v158
	v_fmamk_f32 v52, v52, 0x34800000, v141
	v_rsq_f32_e32 v53, v52
	s_nop 0
	v_mul_f32_e32 v53, 0xbfb8aa3b, v53
	v_mul_f32_e32 v48, v53, v48
	v_mul_f32_e32 v40, v53, v40
	v_exp_f32_e32 v48, v48
	v_exp_f32_e32 v40, v40
	v_fma_f32 v48, v48, v52, v52
	v_fma_f32 v40, v40, v52, v52
; __device__ __forceinline__ unsigned cvt_pk_bf16(float lo, float hi) { unsigned r; asm volatile("v_cvt_pk_bf16_f32 %0, %1, %2" : "=v"(r) : "v"(lo), "v"(hi)); return r; }
; #define PG8_BAR __builtin_amdgcn_s_barrier()
;     __device__ __forceinline__ void operator()(const f32x4 (&acc)[2][2][4][2], const Unit& u, int wr, int wc, int fr, int fq, const float (&pf)[8]) const {
;         const int row0 = u.pm * BM + wr * 64 + fr, col0 = u.pn * HALF + wc * 32 + 8 * fq;
; #pragma unroll
;         for (int ai = 0; ai < 2; ++ai)
; #pragma unroll
;             for (int m = 0; m < 4; ++m) { const int row = row0 + ai * HALF + m * 16;
;                 const float c = (float)__float_as_uint(pf[ai * 4 + m]) * (INV_D / SSQ_SCALE) + RMS_EPS_C, k1 = __builtin_amdgcn_rsqf(c) * -1.4426950408889634f;
;                 float o[8];
; #pragma unroll
;                 for (int e = 0; e < 8; ++e) { const float a = acc[ai][0][m][e >> 2][e & 3], b = acc[ai][1][m][e >> 2][e & 3];
;                     o[e] = (a * b) * __builtin_amdgcn_rcpf(__builtin_fmaf(__builtin_amdgcn_exp2f(a * k1), c, c)); }
;                 u32x4 w; w.x = cvt_pk_bf16(o[0], o[1]); w.y = cvt_pk_bf16(o[2], o[3]); w.z = cvt_pk_bf16(o[4], o[5]); w.w = cvt_pk_bf16(o[6], o[7]);
;                 *(u32x4*)(H + (size_t)row * ldh + col0) = w; }
; template <class Epi, class Sched, bool ALIGN_EPI = false, bool SP2 = false>
; __device__ __forceinline__ void gemm_phase(PG8_LAS unsigned char* lds, const Gemm g, const Sched& S, const Epi& E) {
;     ...
;         if (!has_next) break;
; #pragma unroll
;         for (int a = 0; a < 2; ++a)
; #pragma unroll
;             for (int b = 0; b < 2; ++b)
; #pragma unroll
;                 for (int m = 0; m < 4; ++m)
; #pragma unroll
;                     for (int n = 0; n < 2; ++n) acc[a][b][m][n] = (f32x4){0.f, 0.f, 0.f, 0.f};
;         cur = nxt; cA = nA; cB = nB; ++ui;
;         if constexpr (Epi::PREFETCH) E.prefetch(cur, wr, fr, pf);
;         if constexpr (ALIGN_EPI) { if (wr == 1) PG8_BAR; }
	v_rcp_f32_e32 v48, v48
	v_rcp_f32_e32 v40, v40
	v_mul_f32_e32 v44, v48, v44
	v_mul_f32_e32 v48, v53, v49
	v_mul_f32_e32 v40, v40, v36
	v_mul_f32_e32 v36, v41, v37
	v_mul_f32_e32 v37, v53, v41
	v_exp_f32_e32 v48, v48
	v_exp_f32_e32 v37, v37
	v_fma_f32 v48, v48, v52, v52
	v_fma_f32 v37, v37, v52, v52
	v_rcp_f32_e32 v48, v48
	v_rcp_f32_e32 v37, v37
	v_mul_f32_e32 v45, v48, v45
	v_mul_f32_e32 v48, v53, v50
	v_mul_f32_e32 v41, v37, v36
	v_mul_f32_e32 v37, v53, v42
	v_exp_f32_e32 v48, v48
	v_exp_f32_e32 v37, v37
	v_mul_f32_e32 v36, v42, v38
	v_fma_f32 v48, v48, v52, v52
	v_fma_f32 v37, v37, v52, v52
	v_rcp_f32_e32 v48, v48
	v_rcp_f32_e32 v37, v37
	v_mul_f32_e32 v46, v48, v46
	v_mul_f32_e32 v48, v53, v51
	v_mul_f32_e32 v42, v37, v36
	v_mul_f32_e32 v37, v53, v43
	v_exp_f32_e32 v48, v48
	v_exp_f32_e32 v37, v37
	v_mul_f32_e32 v36, v43, v39
	v_add_u32_e32 v43, 0x90, v161
	v_fma_f32 v48, v48, v52, v52
	v_fmac_f32_e32 v52, v37, v52
	v_rcp_f32_e32 v48, v48
	v_rcp_f32_e32 v37, v52
	v_mul_f32_e32 v47, v48, v47
	v_mul_f32_e32 v39, v37, v36
	v_cvt_pk_bf16_f32 v36, v44, v45
	v_cvt_pk_bf16_f32 v37, v46, v47
	v_cvt_pk_bf16_f32 v38, v40, v41
	v_mad_i64_i32 v[40:41], s[16:17], v43, s58, v[116:117]
	v_lshl_add_u64 v[40:41], v[40:41], 0, v[118:119]
	v_cvt_pk_bf16_f32 v39, v42, v39
	global_store_dwordx4 v[40:41], v[36:39], off
	s_nop 1
	v_cvt_f32_u32_e32 v36, v157
	v_fmamk_f32 v36, v36, 0x34800000, v141
	v_rsq_f32_e32 v37, v36
	s_nop 0
	v_mul_f32_e32 v37, 0xbfb8aa3b, v37
	v_mul_f32_e32 v32, v37, v32
	v_mul_f32_e32 v24, v37, v24
	v_exp_f32_e32 v32, v32
	v_exp_f32_e32 v24, v24
	v_fma_f32 v32, v32, v36, v36
	v_fma_f32 v24, v24, v36, v36
	v_rcp_f32_e32 v32, v32
	v_rcp_f32_e32 v24, v24
	v_mul_f32_e32 v28, v32, v28
	v_mul_f32_e32 v32, v37, v33
	v_mul_f32_e32 v24, v24, v20
	v_mul_f32_e32 v20, v25, v21
	v_mul_f32_e32 v21, v37, v25
	v_exp_f32_e32 v32, v32
	v_exp_f32_e32 v21, v21
	v_fma_f32 v32, v32, v36, v36
	v_fma_f32 v21, v21, v36, v36
	v_rcp_f32_e32 v32, v32
	v_rcp_f32_e32 v21, v21
	v_mul_f32_e32 v29, v32, v29
	v_mul_f32_e32 v32, v37, v34
	v_mul_f32_e32 v25, v21, v20
	v_mul_f32_e32 v21, v37, v26
	v_exp_f32_e32 v32, v32
	v_exp_f32_e32 v21, v21
	v_mul_f32_e32 v20, v26, v22
	v_fma_f32 v32, v32, v36, v36
	v_fma_f32 v21, v21, v36, v36
	v_rcp_f32_e32 v32, v32
	v_rcp_f32_e32 v21, v21
	v_mul_f32_e32 v30, v32, v30
	v_mul_f32_e32 v32, v37, v35
	v_mul_f32_e32 v26, v21, v20
	v_mul_f32_e32 v21, v37, v27
	v_exp_f32_e32 v32, v32
	v_exp_f32_e32 v21, v21
	v_mul_f32_e32 v20, v27, v23
	v_add_u32_e32 v27, 0xa0, v161
	v_fma_f32 v32, v32, v36, v36
	v_fmac_f32_e32 v36, v21, v36
	v_rcp_f32_e32 v32, v32
	v_rcp_f32_e32 v21, v36
	v_mul_f32_e32 v31, v32, v31
	v_mul_f32_e32 v23, v21, v20
	v_cvt_pk_bf16_f32 v20, v28, v29
	v_cvt_pk_bf16_f32 v21, v30, v31
	v_cvt_pk_bf16_f32 v22, v24, v25
	v_mad_i64_i32 v[24:25], s[16:17], v27, s58, v[116:117]
	v_lshl_add_u64 v[24:25], v[24:25], 0, v[118:119]
	v_cvt_pk_bf16_f32 v23, v26, v23
	global_store_dwordx4 v[24:25], v[20:23], off
	s_nop 1
	v_cvt_f32_u32_e32 v20, v156
	v_fmamk_f32 v20, v20, 0x34800000, v141
	v_rsq_f32_e32 v21, v20
	s_nop 0
	v_mul_f32_e32 v21, 0xbfb8aa3b, v21
	v_mul_f32_e32 v16, v21, v16
	v_mul_f32_e32 v8, v21, v8
	v_exp_f32_e32 v16, v16
	v_exp_f32_e32 v8, v8
	v_fma_f32 v16, v16, v20, v20
	v_fma_f32 v8, v8, v20, v20
	v_rcp_f32_e32 v16, v16
	v_rcp_f32_e32 v8, v8
	v_mul_f32_e32 v12, v16, v12
	v_mul_f32_e32 v16, v21, v17
	v_mul_f32_e32 v8, v8, v4
	v_mul_f32_e32 v4, v9, v5
	v_mul_f32_e32 v5, v21, v9
	v_exp_f32_e32 v16, v16
	v_exp_f32_e32 v5, v5
	v_fma_f32 v16, v16, v20, v20
	v_fma_f32 v5, v5, v20, v20
	v_rcp_f32_e32 v16, v16
	v_rcp_f32_e32 v5, v5
	v_mul_f32_e32 v13, v16, v13
	v_mul_f32_e32 v16, v21, v18
	v_mul_f32_e32 v9, v5, v4
	v_mul_f32_e32 v5, v21, v10
	v_exp_f32_e32 v16, v16
	v_exp_f32_e32 v5, v5
	v_mul_f32_e32 v4, v10, v6
	v_fma_f32 v16, v16, v20, v20
	v_fma_f32 v5, v5, v20, v20
	v_rcp_f32_e32 v16, v16
	v_rcp_f32_e32 v5, v5
	v_mul_f32_e32 v14, v16, v14
	v_mul_f32_e32 v16, v21, v19
	v_mul_f32_e32 v10, v5, v4
	v_mul_f32_e32 v5, v21, v11
	v_exp_f32_e32 v16, v16
	v_exp_f32_e32 v5, v5
	v_mul_f32_e32 v4, v11, v7
	v_add_u32_e32 v11, 0xb0, v161
	v_fma_f32 v16, v16, v20, v20
	v_fmac_f32_e32 v20, v5, v20
	v_rcp_f32_e32 v16, v16
	v_rcp_f32_e32 v5, v20
	v_mul_f32_e32 v15, v16, v15
	v_mul_f32_e32 v7, v5, v4
	v_cvt_pk_bf16_f32 v4, v12, v13
	v_cvt_pk_bf16_f32 v5, v14, v15
	v_cvt_pk_bf16_f32 v6, v8, v9
	v_mad_i64_i32 v[8:9], s[16:17], v11, s58, v[116:117]
	v_lshl_add_u64 v[8:9], v[8:9], 0, v[118:119]
	s_mov_b64 s[16:17], -1
	v_cvt_pk_bf16_f32 v7, v10, v7
	global_store_dwordx4 v[8:9], v[4:7], off
	s_cbranch_vccnz .LBB0_81
	s_nop 0
	v_lshl_add_u32 v4, s10, 8, v152
	v_readlane_b32 s2, v255, 32
	v_ashrrev_i32_e32 v5, 31, v4
	v_readlane_b32 s3, v255, 33
	s_andn2_b64 vcc, exec, s[4:5]
	s_nop 0
	v_lshl_add_u64 v[4:5], v[4:5], 2, s[2:3]
	global_load_dword v164, v[4:5], off
	global_load_dword v163, v[4:5], off offset:64
	global_load_dword v162, v[4:5], off offset:128
	global_load_dword v160, v[4:5], off offset:192
	global_load_dword v159, v[4:5], off offset:512
	global_load_dword v158, v[4:5], off offset:576
	global_load_dword v157, v[4:5], off offset:640
	global_load_dword v156, v[4:5], off offset:704
	s_cbranch_vccnz .LBB0_80
	s_barrier
	s_branch .LBB0_80

; #define PG8_STAGE(bufoff, gbase, voff) do { _Pragma("unroll") for (int _i = 0; _i < 2; ++_i) \
;         __builtin_amdgcn_global_load_lds((const unsigned*)((const char*)(gbase) + (voff)[_i]), (PG8_LAS unsigned*)(lds + (bufoff) + ldsw + _i * 8192), 16, 0, 0); } while (0)
; #define PG8_LDA(dst, b, h) do { _Pragma("unroll") for (int m = 0; m < 4; ++m) _Pragma("unroll") for (int k = 0; k < 2; ++k) dst[m][k] = *(const PG8_LAS bf16x8*)(lds + PG8_SA(b, h) + aoff + m * 2048 + k * 1024); } while (0)
; #define PG8_LDB(dst, b, h) do { _Pragma("unroll") for (int n = 0; n < 2; ++n) _Pragma("unroll") for (int k = 0; k < 2; ++k) dst[n][k] = *(const PG8_LAS bf16x8*)(lds + PG8_SB(b, h) + boff + n * 2048 + k * 1024); } while (0)
; #define PG8_MMA(ai, bj, At, Bt) do { __builtin_amdgcn_s_setprio(1); _Pragma("unroll") for (int m = 0; m < 4; ++m) _Pragma("unroll") for (int n = 0; n < 2; ++n) _Pragma("unroll") for (int k = 0; k < 2; ++k) \
;         acc[ai][bj][m][n] = __builtin_amdgcn_mfma_f32_16x16x32_bf16(Bt[n][k], At[m][k], acc[ai][bj][m][n], 0, 0, 0); __builtin_amdgcn_s_setprio(0); } while (0)
; #define PG8_WAIT_V(n) asm volatile("s_waitcnt vmcnt(" #n ")" ::: "memory")
; #define PG8_WAIT_L(n) asm volatile("s_waitcnt lgkmcnt(" #n ")" ::: "memory")
; #define PG8_BAR __builtin_amdgcn_s_barrier()
; #define PG8_SCHED __builtin_amdgcn_sched_barrier(0)
; template <class Epi, class Sched, bool ALIGN_EPI = false, bool SP2 = false>
; __device__ __forceinline__ void gemm_phase(PG8_LAS unsigned char* lds, const Gemm g, const Sched& S, const Epi& E) {
;     ...
;             PG8_LDB(B0, 0, 0); PG8_LDB(B1, 0, 1); PG8_SCHED; PG8_LDA(At, 0, 0); PG8_STAGE(PG8_SA(1, 1), a1 + hstep, voffA);
;             PG8_WAIT_V(8); PG8_WAIT_L(0); PG8_BAR; PG8_MMA(0, 0, At, B0); PG8_MMA(0, 1, At, B1); PG8_BAR; PG8_SCHED;
;             PG8_LDA(At, 0, 1); PG8_STAGE(PG8_SB(0, 0), b2, voffB); PG8_STAGE(PG8_SB(0, 1), b2 + hstep, voffB); PG8_STAGE(PG8_SA(0, 0), a2, voffA);
;             PG8_WAIT_V(8); PG8_WAIT_L(0); PG8_BAR; PG8_MMA(1, 0, At, B0); PG8_MMA(1, 1, At, B1); PG8_BAR; PG8_SCHED;
.LBB0_166:
	s_add_u32 s51, s16, 0x100
	s_addc_u32 s56, s17, 0
	s_mov_b32 s57, -2
	s_waitcnt lgkmcnt(0)
	s_add_u32 s16, s14, 0x100
	s_addc_u32 s17, s15, 0
	s_add_i32 s63, 0, 0x10000
	s_cmpk_eq_i32 s57, 0x54
	s_cselect_b32 s21, s7, s17
	s_cselect_b32 s20, s6, s16
	s_cselect_b32 s19, s13, s56
	s_cselect_b32 s18, s12, s51
	s_add_i32 s64, 0, 0x14000
	v_add_u32_e32 v162, s63, v185
	v_add_u32_e32 v166, s64, v185
	ds_read_b128 v[132:135], v162
	ds_read_b128 v[136:139], v162 offset:1024
	ds_read_b128 v[158:161], v162 offset:2048
	ds_read_b128 v[162:165], v162 offset:3072
	ds_read_b128 v[188:191], v166
	ds_read_b128 v[192:195], v166 offset:1024
	ds_read_b128 v[196:199], v166 offset:2048
	ds_read_b128 v[200:203], v166 offset:3072
	s_add_i32 m0, s26, 0xc000
	ds_read_b128 v[204:207], v187
	ds_read_b128 v[208:211], v187 offset:1024
	ds_read_b128 v[212:215], v187 offset:2048
	ds_read_b128 v[216:219], v187 offset:3072
	ds_read_b128 v[220:223], v187 offset:4096
	ds_read_b128 v[224:227], v187 offset:5120
	ds_read_b128 v[228:231], v187 offset:6144
	ds_read_b128 v[232:235], v187 offset:7168
	global_load_lds_dwordx4 v154, s[14:15]
	s_add_i32 m0, s26, 0xe000
	s_nop 0
	global_load_lds_dwordx4 v156, s[14:15]
	s_waitcnt vmcnt(8)
	s_waitcnt lgkmcnt(0)
	s_setprio 1
	s_barrier
	v_mfma_f32_16x16x32_bf16 v[128:131], v[132:135], v[204:207], 0
	v_mfma_f32_16x16x32_bf16 v[124:127], v[158:161], v[204:207], 0
	v_mfma_f32_16x16x32_bf16 v[112:115], v[132:135], v[212:215], 0
	v_mfma_f32_16x16x32_bf16 v[108:111], v[158:161], v[212:215], 0
	v_mfma_f32_16x16x32_bf16 v[96:99], v[132:135], v[220:223], 0
	v_mfma_f32_16x16x32_bf16 v[92:95], v[158:161], v[220:223], 0
	v_mfma_f32_16x16x32_bf16 v[80:83], v[132:135], v[228:231], 0
	v_mfma_f32_16x16x32_bf16 v[76:79], v[158:161], v[228:231], 0
	v_mfma_f32_16x16x32_bf16 v[128:131], v[136:139], v[208:211], v[128:131]
	v_mfma_f32_16x16x32_bf16 v[124:127], v[162:165], v[208:211], v[124:127]
	v_mfma_f32_16x16x32_bf16 v[112:115], v[136:139], v[216:219], v[112:115]
	v_mfma_f32_16x16x32_bf16 v[108:111], v[162:165], v[216:219], v[108:111]
	v_mfma_f32_16x16x32_bf16 v[96:99], v[136:139], v[224:227], v[96:99]
	v_mfma_f32_16x16x32_bf16 v[92:95], v[162:165], v[224:227], v[92:95]
	v_mfma_f32_16x16x32_bf16 v[80:83], v[136:139], v[232:235], v[80:83]
	v_mfma_f32_16x16x32_bf16 v[76:79], v[162:165], v[232:235], v[76:79]
	v_mfma_f32_16x16x32_bf16 v[120:123], v[188:191], v[204:207], 0
	v_mfma_f32_16x16x32_bf16 v[116:119], v[196:199], v[204:207], 0
	v_mfma_f32_16x16x32_bf16 v[104:107], v[188:191], v[212:215], 0
	v_mfma_f32_16x16x32_bf16 v[100:103], v[196:199], v[212:215], 0
	v_mfma_f32_16x16x32_bf16 v[88:91], v[188:191], v[220:223], 0
	v_mfma_f32_16x16x32_bf16 v[84:87], v[196:199], v[220:223], 0
	v_mfma_f32_16x16x32_bf16 v[72:75], v[188:191], v[228:231], 0
	v_mfma_f32_16x16x32_bf16 v[68:71], v[196:199], v[228:231], 0
	v_mfma_f32_16x16x32_bf16 v[120:123], v[192:195], v[208:211], v[120:123]
	v_mfma_f32_16x16x32_bf16 v[116:119], v[200:203], v[208:211], v[116:119]
	v_mfma_f32_16x16x32_bf16 v[104:107], v[192:195], v[216:219], v[104:107]
	v_mfma_f32_16x16x32_bf16 v[100:103], v[200:203], v[216:219], v[100:103]
	v_mfma_f32_16x16x32_bf16 v[88:91], v[192:195], v[224:227], v[88:91]
	v_mfma_f32_16x16x32_bf16 v[84:87], v[200:203], v[224:227], v[84:87]
	v_mfma_f32_16x16x32_bf16 v[72:75], v[192:195], v[232:235], v[72:75]
	v_mfma_f32_16x16x32_bf16 v[68:71], v[200:203], v[232:235], v[68:71]
	s_barrier
	s_setprio 0
	s_add_i32 s14, s63, s25
	s_mov_b32 m0, s14
	ds_read_b128 v[204:207], v187 offset:16384
	ds_read_b128 v[208:211], v187 offset:17408
	ds_read_b128 v[212:215], v187 offset:18432
	ds_read_b128 v[216:219], v187 offset:19456
	ds_read_b128 v[220:223], v187 offset:20480
	ds_read_b128 v[224:227], v187 offset:21504
	ds_read_b128 v[228:231], v187 offset:22528
	ds_read_b128 v[232:235], v187 offset:23552
	global_load_lds_dwordx4 v2, s[18:19]
	s_add_i32 m0, s14, 0x2000
	s_add_u32 s14, s18, 0x160000
	v_lshl_add_u64 v[236:237], s[18:19], 0, v[152:153]
	s_addc_u32 s15, s19, 0
	s_add_i32 s63, s64, s25
	global_load_lds_dwordx4 v[236:237], off
	s_mov_b32 m0, s63
	s_nop 0
	global_load_lds_dwordx4 v2, s[14:15]
	s_add_i32 m0, s63, 0x2000
	s_nop 0
	global_load_lds_dwordx4 v152, s[14:15]
	s_mov_b32 m0, s26
	s_nop 0
	global_load_lds_dwordx4 v0, s[20:21]
	s_mov_b32 m0, s27
	s_nop 0
	global_load_lds_dwordx4 v150, s[20:21]
	s_waitcnt vmcnt(8)
	s_waitcnt lgkmcnt(0)
	s_setprio 1
	s_barrier
	v_mfma_f32_16x16x32_bf16 v[64:67], v[132:135], v[204:207], 0
	v_mfma_f32_16x16x32_bf16 v[60:63], v[158:161], v[204:207], 0
	v_mfma_f32_16x16x32_bf16 v[48:51], v[132:135], v[212:215], 0
	v_mfma_f32_16x16x32_bf16 v[44:47], v[158:161], v[212:215], 0
	v_mfma_f32_16x16x32_bf16 v[32:35], v[132:135], v[220:223], 0
	v_mfma_f32_16x16x32_bf16 v[28:31], v[158:161], v[220:223], 0
	v_mfma_f32_16x16x32_bf16 v[16:19], v[132:135], v[228:231], 0
	v_mfma_f32_16x16x32_bf16 v[12:15], v[158:161], v[228:231], 0
	v_mfma_f32_16x16x32_bf16 v[64:67], v[136:139], v[208:211], v[64:67]
	v_mfma_f32_16x16x32_bf16 v[60:63], v[162:165], v[208:211], v[60:63]
	v_mfma_f32_16x16x32_bf16 v[48:51], v[136:139], v[216:219], v[48:51]
	v_mfma_f32_16x16x32_bf16 v[44:47], v[162:165], v[216:219], v[44:47]
	v_mfma_f32_16x16x32_bf16 v[32:35], v[136:139], v[224:227], v[32:35]
	v_mfma_f32_16x16x32_bf16 v[28:31], v[162:165], v[224:227], v[28:31]
	v_mfma_f32_16x16x32_bf16 v[16:19], v[136:139], v[232:235], v[16:19]
	v_mfma_f32_16x16x32_bf16 v[12:15], v[162:165], v[232:235], v[12:15]
	v_mfma_f32_16x16x32_bf16 v[56:59], v[188:191], v[204:207], 0
	v_mfma_f32_16x16x32_bf16 v[52:55], v[196:199], v[204:207], 0
	v_mfma_f32_16x16x32_bf16 v[40:43], v[188:191], v[212:215], 0
	v_mfma_f32_16x16x32_bf16 v[36:39], v[196:199], v[212:215], 0
	v_mfma_f32_16x16x32_bf16 v[24:27], v[188:191], v[220:223], 0
	v_mfma_f32_16x16x32_bf16 v[20:23], v[196:199], v[220:223], 0
	v_mfma_f32_16x16x32_bf16 v[8:11], v[188:191], v[228:231], 0
	v_mfma_f32_16x16x32_bf16 v[4:7], v[196:199], v[228:231], 0
	v_mfma_f32_16x16x32_bf16 v[56:59], v[192:195], v[208:211], v[56:59]
	v_mfma_f32_16x16x32_bf16 v[52:55], v[200:203], v[208:211], v[52:55]
	v_mfma_f32_16x16x32_bf16 v[40:43], v[192:195], v[216:219], v[40:43]
	v_mfma_f32_16x16x32_bf16 v[36:39], v[200:203], v[216:219], v[36:39]
	v_mfma_f32_16x16x32_bf16 v[24:27], v[192:195], v[224:227], v[24:27]
	v_mfma_f32_16x16x32_bf16 v[20:23], v[200:203], v[224:227], v[20:23]
	v_mfma_f32_16x16x32_bf16 v[8:11], v[192:195], v[232:235], v[8:11]
	v_mfma_f32_16x16x32_bf16 v[4:7], v[200:203], v[232:235], v[4:7]
	s_barrier
; #define PG8_STAGE(bufoff, gbase, voff) do { _Pragma("unroll") for (int _i = 0; _i < 2; ++_i) \
;         __builtin_amdgcn_global_load_lds((const unsigned*)((const char*)(gbase) + (voff)[_i]), (PG8_LAS unsigned*)(lds + (bufoff) + ldsw + _i * 8192), 16, 0, 0); } while (0)
; #define PG8_LDA(dst, b, h) do { _Pragma("unroll") for (int m = 0; m < 4; ++m) _Pragma("unroll") for (int k = 0; k < 2; ++k) dst[m][k] = *(const PG8_LAS bf16x8*)(lds + PG8_SA(b, h) + aoff + m * 2048 + k * 1024); } while (0)
; #define PG8_LDB(dst, b, h) do { _Pragma("unroll") for (int n = 0; n < 2; ++n) _Pragma("unroll") for (int k = 0; k < 2; ++k) dst[n][k] = *(const PG8_LAS bf16x8*)(lds + PG8_SB(b, h) + boff + n * 2048 + k * 1024); } while (0)
; #define PG8_MMA(ai, bj, At, Bt) do { __builtin_amdgcn_s_setprio(1); _Pragma("unroll") for (int m = 0; m < 4; ++m) _Pragma("unroll") for (int n = 0; n < 2; ++n) _Pragma("unroll") for (int k = 0; k < 2; ++k) \
;         acc[ai][bj][m][n] = __builtin_amdgcn_mfma_f32_16x16x32_bf16(Bt[n][k], At[m][k], acc[ai][bj][m][n], 0, 0, 0); __builtin_amdgcn_s_setprio(0); } while (0)
; #define PG8_WAIT_V(n) asm volatile("s_waitcnt vmcnt(" #n ")" ::: "memory")
; #define PG8_WAIT_L(n) asm volatile("s_waitcnt lgkmcnt(" #n ")" ::: "memory")
; #define PG8_BAR __builtin_amdgcn_s_barrier()
; #define PG8_SCHED __builtin_amdgcn_sched_barrier(0)
; template <class Epi, class Sched, bool ALIGN_EPI = false, bool SP2 = false>
; __device__ __forceinline__ void gemm_phase(PG8_LAS unsigned char* lds, const Gemm g, const Sched& S, const Epi& E) {
;     ...
;             PG8_LDB(B0, 1, 0); PG8_LDB(B1, 1, 1); PG8_SCHED; PG8_LDA(At, 1, 0); PG8_STAGE(PG8_SA(0, 1), a2 + hstep, voffA);
;             PG8_WAIT_V(8); PG8_WAIT_L(0); PG8_BAR; PG8_MMA(0, 0, At, B0); PG8_MMA(0, 1, At, B1); PG8_BAR; PG8_SCHED;
;             PG8_LDA(At, 1, 1); PG8_STAGE(PG8_SB(1, 0), b3, voffB); PG8_STAGE(PG8_SB(1, 1), b3 + hstep, voffB); PG8_STAGE(PG8_SA(1, 0), a3, voffA);
;             PG8_WAIT_V(8); PG8_WAIT_L(0); PG8_BAR; PG8_MMA(1, 0, At, B0); PG8_MMA(1, 1, At, B1); PG8_BAR; PG8_SCHED;
	s_setprio 0
	s_add_i32 s63, 0, 0x18000
	s_add_i32 s64, 0, 0x1c000
	v_add_u32_e32 v162, s63, v185
	v_add_u32_e32 v200, s64, v185
	ds_read_b128 v[132:135], v162
	ds_read_b128 v[136:139], v162 offset:1024
	ds_read_b128 v[158:161], v162 offset:2048
	ds_read_b128 v[162:165], v162 offset:3072
	ds_read_b128 v[188:191], v200
	ds_read_b128 v[192:195], v200 offset:1024
	ds_read_b128 v[196:199], v200 offset:2048
	ds_read_b128 v[200:203], v200 offset:3072
	s_add_u32 s14, s20, 0x160000
	s_addc_u32 s15, s21, 0
	s_mov_b32 m0, s28
	ds_read_b128 v[204:207], v187 offset:32768
	ds_read_b128 v[208:211], v187 offset:33792
	ds_read_b128 v[212:215], v187 offset:34816
	ds_read_b128 v[216:219], v187 offset:35840
	ds_read_b128 v[220:223], v187 offset:36864
	ds_read_b128 v[224:227], v187 offset:37888
	ds_read_b128 v[228:231], v187 offset:38912
	ds_read_b128 v[232:235], v187 offset:39936
	global_load_lds_dwordx4 v0, s[14:15]
	s_mov_b32 m0, s29
	s_nop 0
	global_load_lds_dwordx4 v150, s[14:15]
	s_waitcnt vmcnt(8)
	s_waitcnt lgkmcnt(0)
	s_setprio 1
	s_barrier
	v_mfma_f32_16x16x32_bf16 v[128:131], v[132:135], v[204:207], v[128:131]
	v_mfma_f32_16x16x32_bf16 v[124:127], v[158:161], v[204:207], v[124:127]
	v_mfma_f32_16x16x32_bf16 v[112:115], v[132:135], v[212:215], v[112:115]
	v_mfma_f32_16x16x32_bf16 v[108:111], v[158:161], v[212:215], v[108:111]
	v_mfma_f32_16x16x32_bf16 v[96:99], v[132:135], v[220:223], v[96:99]
	v_mfma_f32_16x16x32_bf16 v[92:95], v[158:161], v[220:223], v[92:95]
	v_mfma_f32_16x16x32_bf16 v[80:83], v[132:135], v[228:231], v[80:83]
	v_mfma_f32_16x16x32_bf16 v[76:79], v[158:161], v[228:231], v[76:79]
	v_mfma_f32_16x16x32_bf16 v[128:131], v[136:139], v[208:211], v[128:131]
	v_mfma_f32_16x16x32_bf16 v[124:127], v[162:165], v[208:211], v[124:127]
	v_mfma_f32_16x16x32_bf16 v[112:115], v[136:139], v[216:219], v[112:115]
	v_mfma_f32_16x16x32_bf16 v[108:111], v[162:165], v[216:219], v[108:111]
	v_mfma_f32_16x16x32_bf16 v[96:99], v[136:139], v[224:227], v[96:99]
	v_mfma_f32_16x16x32_bf16 v[92:95], v[162:165], v[224:227], v[92:95]
	v_mfma_f32_16x16x32_bf16 v[80:83], v[136:139], v[232:235], v[80:83]
	v_mfma_f32_16x16x32_bf16 v[76:79], v[162:165], v[232:235], v[76:79]
	v_mfma_f32_16x16x32_bf16 v[120:123], v[188:191], v[204:207], v[120:123]
	v_mfma_f32_16x16x32_bf16 v[116:119], v[196:199], v[204:207], v[116:119]
	v_mfma_f32_16x16x32_bf16 v[104:107], v[188:191], v[212:215], v[104:107]
	v_mfma_f32_16x16x32_bf16 v[100:103], v[196:199], v[212:215], v[100:103]
	v_mfma_f32_16x16x32_bf16 v[88:91], v[188:191], v[220:223], v[88:91]
	v_mfma_f32_16x16x32_bf16 v[84:87], v[196:199], v[220:223], v[84:87]
	v_mfma_f32_16x16x32_bf16 v[72:75], v[188:191], v[228:231], v[72:75]
	v_mfma_f32_16x16x32_bf16 v[68:71], v[196:199], v[228:231], v[68:71]
	v_mfma_f32_16x16x32_bf16 v[120:123], v[192:195], v[208:211], v[120:123]
	v_mfma_f32_16x16x32_bf16 v[116:119], v[200:203], v[208:211], v[116:119]
	v_mfma_f32_16x16x32_bf16 v[104:107], v[192:195], v[216:219], v[104:107]
	v_mfma_f32_16x16x32_bf16 v[100:103], v[200:203], v[216:219], v[100:103]
	v_mfma_f32_16x16x32_bf16 v[88:91], v[192:195], v[224:227], v[88:91]
	v_mfma_f32_16x16x32_bf16 v[84:87], v[200:203], v[224:227], v[84:87]
	v_mfma_f32_16x16x32_bf16 v[72:75], v[192:195], v[232:235], v[72:75]
	v_mfma_f32_16x16x32_bf16 v[68:71], v[200:203], v[232:235], v[68:71]
	s_barrier
	s_setprio 0
	s_add_i32 s14, s63, s25
	s_mov_b32 m0, s14
	ds_read_b128 v[204:207], v187 offset:49152
	ds_read_b128 v[208:211], v187 offset:50176
	ds_read_b128 v[212:215], v187 offset:51200
	ds_read_b128 v[216:219], v187 offset:52224
	ds_read_b128 v[220:223], v187 offset:53248
	ds_read_b128 v[224:227], v187 offset:54272
	ds_read_b128 v[228:231], v187 offset:55296
	ds_read_b128 v[232:235], v187 offset:56320
	s_add_u32 vcc_lo, s18, 0x80
	s_addc_u32 vcc_hi, s19, 0
	global_load_lds_dwordx4 v2, vcc
	s_add_i32 m0, s14, 0x2000
	s_add_u32 s14, s18, 0x160080
	v_lshl_add_u64 v[166:167], v[236:237], 0, s[36:37]
	s_addc_u32 s15, s19, 0
	s_add_i32 s18, s64, s25
	global_load_lds_dwordx4 v[166:167], off
	s_mov_b32 m0, s18
	s_nop 0
	global_load_lds_dwordx4 v2, s[14:15]
	v_lshl_add_u64 v[166:167], s[14:15], 0, v[152:153]
	s_add_i32 m0, s18, 0x2000
	s_nop 0
	global_load_lds_dwordx4 v[166:167], off
	s_mov_b32 m0, s30
	s_nop 0
	s_add_u32 vcc_lo, s20, 0x80
	s_addc_u32 vcc_hi, s21, 0
	global_load_lds_dwordx4 v0, vcc
	s_mov_b32 m0, s31
	s_nop 0
	s_add_u32 vcc_lo, s20, 0x80
	s_addc_u32 vcc_hi, s21, 0
	global_load_lds_dwordx4 v150, vcc
	s_waitcnt vmcnt(8)
	s_waitcnt lgkmcnt(0)
	s_setprio 1
	s_barrier
	v_mfma_f32_16x16x32_bf16 v[64:67], v[132:135], v[204:207], v[64:67]
	v_mfma_f32_16x16x32_bf16 v[60:63], v[158:161], v[204:207], v[60:63]
	v_mfma_f32_16x16x32_bf16 v[48:51], v[132:135], v[212:215], v[48:51]
	v_mfma_f32_16x16x32_bf16 v[44:47], v[158:161], v[212:215], v[44:47]
	v_mfma_f32_16x16x32_bf16 v[32:35], v[132:135], v[220:223], v[32:35]
	v_mfma_f32_16x16x32_bf16 v[28:31], v[158:161], v[220:223], v[28:31]
	v_mfma_f32_16x16x32_bf16 v[16:19], v[132:135], v[228:231], v[16:19]
	v_mfma_f32_16x16x32_bf16 v[12:15], v[158:161], v[228:231], v[12:15]
	v_mfma_f32_16x16x32_bf16 v[64:67], v[136:139], v[208:211], v[64:67]
	v_mfma_f32_16x16x32_bf16 v[60:63], v[162:165], v[208:211], v[60:63]
	v_mfma_f32_16x16x32_bf16 v[48:51], v[136:139], v[216:219], v[48:51]
	v_mfma_f32_16x16x32_bf16 v[44:47], v[162:165], v[216:219], v[44:47]
	v_mfma_f32_16x16x32_bf16 v[32:35], v[136:139], v[224:227], v[32:35]
	v_mfma_f32_16x16x32_bf16 v[28:31], v[162:165], v[224:227], v[28:31]
	v_mfma_f32_16x16x32_bf16 v[16:19], v[136:139], v[232:235], v[16:19]
	v_mfma_f32_16x16x32_bf16 v[12:15], v[162:165], v[232:235], v[12:15]
	v_mfma_f32_16x16x32_bf16 v[56:59], v[188:191], v[204:207], v[56:59]
	v_mfma_f32_16x16x32_bf16 v[52:55], v[196:199], v[204:207], v[52:55]
	v_mfma_f32_16x16x32_bf16 v[40:43], v[188:191], v[212:215], v[40:43]
	v_mfma_f32_16x16x32_bf16 v[36:39], v[196:199], v[212:215], v[36:39]
	v_mfma_f32_16x16x32_bf16 v[24:27], v[188:191], v[220:223], v[24:27]
	v_mfma_f32_16x16x32_bf16 v[20:23], v[196:199], v[220:223], v[20:23]
	v_mfma_f32_16x16x32_bf16 v[8:11], v[188:191], v[228:231], v[8:11]
	v_mfma_f32_16x16x32_bf16 v[4:7], v[196:199], v[228:231], v[4:7]
	v_mfma_f32_16x16x32_bf16 v[56:59], v[192:195], v[208:211], v[56:59]
	v_mfma_f32_16x16x32_bf16 v[52:55], v[200:203], v[208:211], v[52:55]
	v_mfma_f32_16x16x32_bf16 v[40:43], v[192:195], v[216:219], v[40:43]
	v_mfma_f32_16x16x32_bf16 v[36:39], v[200:203], v[216:219], v[36:39]
	v_mfma_f32_16x16x32_bf16 v[24:27], v[192:195], v[224:227], v[24:27]
	v_mfma_f32_16x16x32_bf16 v[20:23], v[200:203], v[224:227], v[20:23]
	v_mfma_f32_16x16x32_bf16 v[8:11], v[192:195], v[232:235], v[8:11]
	v_mfma_f32_16x16x32_bf16 v[4:7], v[200:203], v[232:235], v[4:7]
	s_barrier
	s_setprio 0
	s_add_i32 s57, s57, 2
	s_add_u32 s51, s51, 0x100
	s_addc_u32 s56, s56, 0
	s_cmpk_gt_u32 s57, 0x55
	s_mov_b64 s[14:15], s[16:17]
; #define PG8_STAGE(bufoff, gbase, voff) do { _Pragma("unroll") for (int _i = 0; _i < 2; ++_i) \
;         __builtin_amdgcn_global_load_lds((const unsigned*)((const char*)(gbase) + (voff)[_i]), (PG8_LAS unsigned*)(lds + (bufoff) + ldsw + _i * 8192), 16, 0, 0); } while (0)
; #define PG8_LDA(dst, b, h) do { _Pragma("unroll") for (int m = 0; m < 4; ++m) _Pragma("unroll") for (int k = 0; k < 2; ++k) dst[m][k] = *(const PG8_LAS bf16x8*)(lds + PG8_SA(b, h) + aoff + m * 2048 + k * 1024); } while (0)
; #define PG8_LDB(dst, b, h) do { _Pragma("unroll") for (int n = 0; n < 2; ++n) _Pragma("unroll") for (int k = 0; k < 2; ++k) dst[n][k] = *(const PG8_LAS bf16x8*)(lds + PG8_SB(b, h) + boff + n * 2048 + k * 1024); } while (0)
; #define PG8_MMA(ai, bj, At, Bt) do { __builtin_amdgcn_s_setprio(1); _Pragma("unroll") for (int m = 0; m < 4; ++m) _Pragma("unroll") for (int n = 0; n < 2; ++n) _Pragma("unroll") for (int k = 0; k < 2; ++k) \
;         acc[ai][bj][m][n] = __builtin_amdgcn_mfma_f32_16x16x32_bf16(Bt[n][k], At[m][k], acc[ai][bj][m][n], 0, 0, 0); __builtin_amdgcn_s_setprio(0); } while (0)
; #define PG8_WAIT_V(n) asm volatile("s_waitcnt vmcnt(" #n ")" ::: "memory")
; #define PG8_WAIT_L(n) asm volatile("s_waitcnt lgkmcnt(" #n ")" ::: "memory")
; #define PG8_BAR __builtin_amdgcn_s_barrier()
; #define PG8_SCHED __builtin_amdgcn_sched_barrier(0)
; template <class Epi, class Sched, bool ALIGN_EPI = false, bool SP2 = false>
; __device__ __forceinline__ void gemm_phase(PG8_LAS unsigned char* lds, const Gemm g, const Sched& S, const Epi& E) {
;     ...
;             PG8_LDB(B0, 0, 0); PG8_LDB(B1, 0, 1); PG8_SCHED; PG8_LDA(At, 0, 0); PG8_STAGE(PG8_SA(1, 1), a1 + hstep, voffA);
;             PG8_WAIT_V(8); PG8_WAIT_L(0); PG8_BAR; PG8_MMA(0, 0, At, B0); PG8_MMA(0, 1, At, B1); PG8_BAR; PG8_SCHED;
;             PG8_LDA(At, 0, 1); PG8_STAGE(PG8_SB(0, 0), b2, voffB); PG8_STAGE(PG8_SB(0, 1), b2 + hstep, voffB); PG8_STAGE(PG8_SA(0, 0), a2, voffA);
;             PG8_WAIT_V(8); PG8_WAIT_L(0); PG8_BAR; PG8_MMA(1, 0, At, B0); PG8_MMA(1, 1, At, B1); PG8_BAR; PG8_SCHED;
.LBB0_167:
	s_add_u32 s16, s14, 0x100
	s_addc_u32 s17, s15, 0
	s_add_i32 s63, 0, 0x10000
	s_cmpk_eq_i32 s57, 0x54
	s_cselect_b32 s21, s7, s17
	s_cselect_b32 s20, s6, s16
	s_cselect_b32 s19, s13, s56
	s_cselect_b32 s18, s12, s51
	s_add_i32 s64, 0, 0x14000
	v_add_u32_e32 v162, s63, v185
	v_add_u32_e32 v166, s64, v185
	ds_read_b128 v[132:135], v162
	ds_read_b128 v[136:139], v162 offset:1024
	ds_read_b128 v[158:161], v162 offset:2048
	ds_read_b128 v[162:165], v162 offset:3072
	ds_read_b128 v[188:191], v166
	ds_read_b128 v[192:195], v166 offset:1024
	ds_read_b128 v[196:199], v166 offset:2048
	ds_read_b128 v[200:203], v166 offset:3072
	s_add_i32 m0, s26, 0xc000
	ds_read_b128 v[204:207], v187
	ds_read_b128 v[208:211], v187 offset:1024
	ds_read_b128 v[212:215], v187 offset:2048
	ds_read_b128 v[216:219], v187 offset:3072
	ds_read_b128 v[220:223], v187 offset:4096
	ds_read_b128 v[224:227], v187 offset:5120
	ds_read_b128 v[228:231], v187 offset:6144
	ds_read_b128 v[232:235], v187 offset:7168
	global_load_lds_dwordx4 v154, s[14:15]
	s_add_i32 m0, s26, 0xe000
	s_nop 0
	global_load_lds_dwordx4 v156, s[14:15]
	s_waitcnt vmcnt(8)
	s_waitcnt lgkmcnt(0)
	s_setprio 1
	s_barrier
	v_mfma_f32_16x16x32_bf16 v[128:131], v[132:135], v[204:207], v[128:131]
	v_mfma_f32_16x16x32_bf16 v[124:127], v[158:161], v[204:207], v[124:127]
	v_mfma_f32_16x16x32_bf16 v[112:115], v[132:135], v[212:215], v[112:115]
	v_mfma_f32_16x16x32_bf16 v[108:111], v[158:161], v[212:215], v[108:111]
	v_mfma_f32_16x16x32_bf16 v[96:99], v[132:135], v[220:223], v[96:99]
	v_mfma_f32_16x16x32_bf16 v[92:95], v[158:161], v[220:223], v[92:95]
	v_mfma_f32_16x16x32_bf16 v[80:83], v[132:135], v[228:231], v[80:83]
	v_mfma_f32_16x16x32_bf16 v[76:79], v[158:161], v[228:231], v[76:79]
	v_mfma_f32_16x16x32_bf16 v[128:131], v[136:139], v[208:211], v[128:131]
	v_mfma_f32_16x16x32_bf16 v[124:127], v[162:165], v[208:211], v[124:127]
	v_mfma_f32_16x16x32_bf16 v[112:115], v[136:139], v[216:219], v[112:115]
	v_mfma_f32_16x16x32_bf16 v[108:111], v[162:165], v[216:219], v[108:111]
	v_mfma_f32_16x16x32_bf16 v[96:99], v[136:139], v[224:227], v[96:99]
	v_mfma_f32_16x16x32_bf16 v[92:95], v[162:165], v[224:227], v[92:95]
	v_mfma_f32_16x16x32_bf16 v[80:83], v[136:139], v[232:235], v[80:83]
	v_mfma_f32_16x16x32_bf16 v[76:79], v[162:165], v[232:235], v[76:79]
	v_mfma_f32_16x16x32_bf16 v[120:123], v[188:191], v[204:207], v[120:123]
	v_mfma_f32_16x16x32_bf16 v[116:119], v[196:199], v[204:207], v[116:119]
	v_mfma_f32_16x16x32_bf16 v[104:107], v[188:191], v[212:215], v[104:107]
	v_mfma_f32_16x16x32_bf16 v[100:103], v[196:199], v[212:215], v[100:103]
	v_mfma_f32_16x16x32_bf16 v[88:91], v[188:191], v[220:223], v[88:91]
	v_mfma_f32_16x16x32_bf16 v[84:87], v[196:199], v[220:223], v[84:87]
	v_mfma_f32_16x16x32_bf16 v[72:75], v[188:191], v[228:231], v[72:75]
	v_mfma_f32_16x16x32_bf16 v[68:71], v[196:199], v[228:231], v[68:71]
	v_mfma_f32_16x16x32_bf16 v[120:123], v[192:195], v[208:211], v[120:123]
	v_mfma_f32_16x16x32_bf16 v[116:119], v[200:203], v[208:211], v[116:119]
	v_mfma_f32_16x16x32_bf16 v[104:107], v[192:195], v[216:219], v[104:107]
	v_mfma_f32_16x16x32_bf16 v[100:103], v[200:203], v[216:219], v[100:103]
	v_mfma_f32_16x16x32_bf16 v[88:91], v[192:195], v[224:227], v[88:91]
	v_mfma_f32_16x16x32_bf16 v[84:87], v[200:203], v[224:227], v[84:87]
	v_mfma_f32_16x16x32_bf16 v[72:75], v[192:195], v[232:235], v[72:75]
	v_mfma_f32_16x16x32_bf16 v[68:71], v[200:203], v[232:235], v[68:71]
	s_barrier
	s_setprio 0
	s_add_i32 s14, s63, s25
	s_mov_b32 m0, s14
	ds_read_b128 v[204:207], v187 offset:16384
	ds_read_b128 v[208:211], v187 offset:17408
	ds_read_b128 v[212:215], v187 offset:18432
	ds_read_b128 v[216:219], v187 offset:19456
	ds_read_b128 v[220:223], v187 offset:20480
	ds_read_b128 v[224:227], v187 offset:21504
	ds_read_b128 v[228:231], v187 offset:22528
	ds_read_b128 v[232:235], v187 offset:23552
	global_load_lds_dwordx4 v2, s[18:19]
	s_add_i32 m0, s14, 0x2000
	s_add_u32 s14, s18, 0x160000
	v_lshl_add_u64 v[236:237], s[18:19], 0, v[152:153]
	s_addc_u32 s15, s19, 0
	s_add_i32 s63, s64, s25
	global_load_lds_dwordx4 v[236:237], off
	s_mov_b32 m0, s63
	s_nop 0
	global_load_lds_dwordx4 v2, s[14:15]
	s_add_i32 m0, s63, 0x2000
	s_nop 0
	global_load_lds_dwordx4 v152, s[14:15]
	s_mov_b32 m0, s26
	s_nop 0
	global_load_lds_dwordx4 v0, s[20:21]
	s_mov_b32 m0, s27
	s_nop 0
	global_load_lds_dwordx4 v150, s[20:21]
	s_waitcnt vmcnt(8)
	s_waitcnt lgkmcnt(0)
	s_setprio 1
	s_barrier
	v_mfma_f32_16x16x32_bf16 v[64:67], v[132:135], v[204:207], v[64:67]
	v_mfma_f32_16x16x32_bf16 v[60:63], v[158:161], v[204:207], v[60:63]
	v_mfma_f32_16x16x32_bf16 v[48:51], v[132:135], v[212:215], v[48:51]
	v_mfma_f32_16x16x32_bf16 v[44:47], v[158:161], v[212:215], v[44:47]
	v_mfma_f32_16x16x32_bf16 v[32:35], v[132:135], v[220:223], v[32:35]
	v_mfma_f32_16x16x32_bf16 v[28:31], v[158:161], v[220:223], v[28:31]
	v_mfma_f32_16x16x32_bf16 v[16:19], v[132:135], v[228:231], v[16:19]
	v_mfma_f32_16x16x32_bf16 v[12:15], v[158:161], v[228:231], v[12:15]
	v_mfma_f32_16x16x32_bf16 v[64:67], v[136:139], v[208:211], v[64:67]
	v_mfma_f32_16x16x32_bf16 v[60:63], v[162:165], v[208:211], v[60:63]
	v_mfma_f32_16x16x32_bf16 v[48:51], v[136:139], v[216:219], v[48:51]
	v_mfma_f32_16x16x32_bf16 v[44:47], v[162:165], v[216:219], v[44:47]
	v_mfma_f32_16x16x32_bf16 v[32:35], v[136:139], v[224:227], v[32:35]
	v_mfma_f32_16x16x32_bf16 v[28:31], v[162:165], v[224:227], v[28:31]
	v_mfma_f32_16x16x32_bf16 v[16:19], v[136:139], v[232:235], v[16:19]
	v_mfma_f32_16x16x32_bf16 v[12:15], v[162:165], v[232:235], v[12:15]
	v_mfma_f32_16x16x32_bf16 v[56:59], v[188:191], v[204:207], v[56:59]
	v_mfma_f32_16x16x32_bf16 v[52:55], v[196:199], v[204:207], v[52:55]
	v_mfma_f32_16x16x32_bf16 v[40:43], v[188:191], v[212:215], v[40:43]
	v_mfma_f32_16x16x32_bf16 v[36:39], v[196:199], v[212:215], v[36:39]
	v_mfma_f32_16x16x32_bf16 v[24:27], v[188:191], v[220:223], v[24:27]
	v_mfma_f32_16x16x32_bf16 v[20:23], v[196:199], v[220:223], v[20:23]
	v_mfma_f32_16x16x32_bf16 v[8:11], v[188:191], v[228:231], v[8:11]
	v_mfma_f32_16x16x32_bf16 v[4:7], v[196:199], v[228:231], v[4:7]
	v_mfma_f32_16x16x32_bf16 v[56:59], v[192:195], v[208:211], v[56:59]
	v_mfma_f32_16x16x32_bf16 v[52:55], v[200:203], v[208:211], v[52:55]
	v_mfma_f32_16x16x32_bf16 v[40:43], v[192:195], v[216:219], v[40:43]
	v_mfma_f32_16x16x32_bf16 v[36:39], v[200:203], v[216:219], v[36:39]
	v_mfma_f32_16x16x32_bf16 v[24:27], v[192:195], v[224:227], v[24:27]
	v_mfma_f32_16x16x32_bf16 v[20:23], v[200:203], v[224:227], v[20:23]
	v_mfma_f32_16x16x32_bf16 v[8:11], v[192:195], v[232:235], v[8:11]
	v_mfma_f32_16x16x32_bf16 v[4:7], v[200:203], v[232:235], v[4:7]
	s_barrier
; #define PG8_STAGE(bufoff, gbase, voff) do { _Pragma("unroll") for (int _i = 0; _i < 2; ++_i) \
;         __builtin_amdgcn_global_load_lds((const unsigned*)((const char*)(gbase) + (voff)[_i]), (PG8_LAS unsigned*)(lds + (bufoff) + ldsw + _i * 8192), 16, 0, 0); } while (0)
; #define PG8_LDA(dst, b, h) do { _Pragma("unroll") for (int m = 0; m < 4; ++m) _Pragma("unroll") for (int k = 0; k < 2; ++k) dst[m][k] = *(const PG8_LAS bf16x8*)(lds + PG8_SA(b, h) + aoff + m * 2048 + k * 1024); } while (0)
; #define PG8_LDB(dst, b, h) do { _Pragma("unroll") for (int n = 0; n < 2; ++n) _Pragma("unroll") for (int k = 0; k < 2; ++k) dst[n][k] = *(const PG8_LAS bf16x8*)(lds + PG8_SB(b, h) + boff + n * 2048 + k * 1024); } while (0)
; #define PG8_MMA(ai, bj, At, Bt) do { __builtin_amdgcn_s_setprio(1); _Pragma("unroll") for (int m = 0; m < 4; ++m) _Pragma("unroll") for (int n = 0; n < 2; ++n) _Pragma("unroll") for (int k = 0; k < 2; ++k) \
;         acc[ai][bj][m][n] = __builtin_amdgcn_mfma_f32_16x16x32_bf16(Bt[n][k], At[m][k], acc[ai][bj][m][n], 0, 0, 0); __builtin_amdgcn_s_setprio(0); } while (0)
; #define PG8_WAIT_V(n) asm volatile("s_waitcnt vmcnt(" #n ")" ::: "memory")
; #define PG8_WAIT_L(n) asm volatile("s_waitcnt lgkmcnt(" #n ")" ::: "memory")
; #define PG8_BAR __builtin_amdgcn_s_barrier()
; #define PG8_SCHED __builtin_amdgcn_sched_barrier(0)
; template <class Epi, class Sched, bool ALIGN_EPI = false, bool SP2 = false>
; __device__ __forceinline__ void gemm_phase(PG8_LAS unsigned char* lds, const Gemm g, const Sched& S, const Epi& E) {
;     ...
;             PG8_LDB(B0, 1, 0); PG8_LDB(B1, 1, 1); PG8_SCHED; PG8_LDA(At, 1, 0); PG8_STAGE(PG8_SA(0, 1), a2 + hstep, voffA);
;             PG8_WAIT_V(8); PG8_WAIT_L(0); PG8_BAR; PG8_MMA(0, 0, At, B0); PG8_MMA(0, 1, At, B1); PG8_BAR; PG8_SCHED;
;             PG8_LDA(At, 1, 1); PG8_STAGE(PG8_SB(1, 0), b3, voffB); PG8_STAGE(PG8_SB(1, 1), b3 + hstep, voffB); PG8_STAGE(PG8_SA(1, 0), a3, voffA);
;             PG8_WAIT_V(8); PG8_WAIT_L(0); PG8_BAR; PG8_MMA(1, 0, At, B0); PG8_MMA(1, 1, At, B1); PG8_BAR; PG8_SCHED;
;     ...
;         if constexpr (ALIGN_EPI) { if (wr == 0) PG8_BAR; }
	s_setprio 0
	s_add_i32 s63, 0, 0x18000
	s_add_i32 s64, 0, 0x1c000
	v_add_u32_e32 v162, s63, v185
	v_add_u32_e32 v200, s64, v185
	ds_read_b128 v[132:135], v162
	ds_read_b128 v[136:139], v162 offset:1024
	ds_read_b128 v[158:161], v162 offset:2048
	ds_read_b128 v[162:165], v162 offset:3072
	ds_read_b128 v[188:191], v200
	ds_read_b128 v[192:195], v200 offset:1024
	ds_read_b128 v[196:199], v200 offset:2048
	ds_read_b128 v[200:203], v200 offset:3072
	s_add_u32 s14, s20, 0x160000
	s_addc_u32 s15, s21, 0
	s_mov_b32 m0, s28
	ds_read_b128 v[204:207], v187 offset:32768
	ds_read_b128 v[208:211], v187 offset:33792
	ds_read_b128 v[212:215], v187 offset:34816
	ds_read_b128 v[216:219], v187 offset:35840
	ds_read_b128 v[220:223], v187 offset:36864
	ds_read_b128 v[224:227], v187 offset:37888
	ds_read_b128 v[228:231], v187 offset:38912
	ds_read_b128 v[232:235], v187 offset:39936
	global_load_lds_dwordx4 v0, s[14:15]
	s_mov_b32 m0, s29
	s_nop 0
	global_load_lds_dwordx4 v150, s[14:15]
	s_waitcnt vmcnt(8)
	s_waitcnt lgkmcnt(0)
	s_setprio 1
	s_barrier
	v_mfma_f32_16x16x32_bf16 v[128:131], v[132:135], v[204:207], v[128:131]
	v_mfma_f32_16x16x32_bf16 v[124:127], v[158:161], v[204:207], v[124:127]
	v_mfma_f32_16x16x32_bf16 v[112:115], v[132:135], v[212:215], v[112:115]
	v_mfma_f32_16x16x32_bf16 v[108:111], v[158:161], v[212:215], v[108:111]
	v_mfma_f32_16x16x32_bf16 v[96:99], v[132:135], v[220:223], v[96:99]
	v_mfma_f32_16x16x32_bf16 v[92:95], v[158:161], v[220:223], v[92:95]
	v_mfma_f32_16x16x32_bf16 v[80:83], v[132:135], v[228:231], v[80:83]
	v_mfma_f32_16x16x32_bf16 v[76:79], v[158:161], v[228:231], v[76:79]
	v_mfma_f32_16x16x32_bf16 v[128:131], v[136:139], v[208:211], v[128:131]
	v_mfma_f32_16x16x32_bf16 v[124:127], v[162:165], v[208:211], v[124:127]
	v_mfma_f32_16x16x32_bf16 v[112:115], v[136:139], v[216:219], v[112:115]
	v_mfma_f32_16x16x32_bf16 v[108:111], v[162:165], v[216:219], v[108:111]
	v_mfma_f32_16x16x32_bf16 v[96:99], v[136:139], v[224:227], v[96:99]
	v_mfma_f32_16x16x32_bf16 v[92:95], v[162:165], v[224:227], v[92:95]
	v_mfma_f32_16x16x32_bf16 v[80:83], v[136:139], v[232:235], v[80:83]
	v_mfma_f32_16x16x32_bf16 v[76:79], v[162:165], v[232:235], v[76:79]
	v_mfma_f32_16x16x32_bf16 v[120:123], v[188:191], v[204:207], v[120:123]
	v_mfma_f32_16x16x32_bf16 v[116:119], v[196:199], v[204:207], v[116:119]
	v_mfma_f32_16x16x32_bf16 v[104:107], v[188:191], v[212:215], v[104:107]
	v_mfma_f32_16x16x32_bf16 v[100:103], v[196:199], v[212:215], v[100:103]
	v_mfma_f32_16x16x32_bf16 v[88:91], v[188:191], v[220:223], v[88:91]
	v_mfma_f32_16x16x32_bf16 v[84:87], v[196:199], v[220:223], v[84:87]
	v_mfma_f32_16x16x32_bf16 v[72:75], v[188:191], v[228:231], v[72:75]
	v_mfma_f32_16x16x32_bf16 v[68:71], v[196:199], v[228:231], v[68:71]
	v_mfma_f32_16x16x32_bf16 v[120:123], v[192:195], v[208:211], v[120:123]
	v_mfma_f32_16x16x32_bf16 v[116:119], v[200:203], v[208:211], v[116:119]
	v_mfma_f32_16x16x32_bf16 v[104:107], v[192:195], v[216:219], v[104:107]
	v_mfma_f32_16x16x32_bf16 v[100:103], v[200:203], v[216:219], v[100:103]
	v_mfma_f32_16x16x32_bf16 v[88:91], v[192:195], v[224:227], v[88:91]
	v_mfma_f32_16x16x32_bf16 v[84:87], v[200:203], v[224:227], v[84:87]
	v_mfma_f32_16x16x32_bf16 v[72:75], v[192:195], v[232:235], v[72:75]
	v_mfma_f32_16x16x32_bf16 v[68:71], v[200:203], v[232:235], v[68:71]
	s_barrier
	s_setprio 0
	s_add_i32 s14, s63, s25
	s_mov_b32 m0, s14
	ds_read_b128 v[204:207], v187 offset:49152
	ds_read_b128 v[208:211], v187 offset:50176
	ds_read_b128 v[212:215], v187 offset:51200
	ds_read_b128 v[216:219], v187 offset:52224
	ds_read_b128 v[220:223], v187 offset:53248
	ds_read_b128 v[224:227], v187 offset:54272
	ds_read_b128 v[228:231], v187 offset:55296
	ds_read_b128 v[232:235], v187 offset:56320
	s_add_u32 vcc_lo, s18, 0x80
	s_addc_u32 vcc_hi, s19, 0
	global_load_lds_dwordx4 v2, vcc
	s_add_i32 m0, s14, 0x2000
	s_add_u32 s14, s18, 0x160080
	v_lshl_add_u64 v[166:167], v[236:237], 0, s[36:37]
	s_addc_u32 s15, s19, 0
	s_add_i32 s18, s64, s25
	global_load_lds_dwordx4 v[166:167], off
	s_mov_b32 m0, s18
	s_nop 0
	global_load_lds_dwordx4 v2, s[14:15]
	v_lshl_add_u64 v[166:167], s[14:15], 0, v[152:153]
	s_add_i32 m0, s18, 0x2000
	s_nop 0
	global_load_lds_dwordx4 v[166:167], off
	s_mov_b32 m0, s30
	s_nop 0
	s_add_u32 vcc_lo, s20, 0x80
	s_addc_u32 vcc_hi, s21, 0
	global_load_lds_dwordx4 v0, vcc
	s_mov_b32 m0, s31
	s_nop 0
	s_add_u32 vcc_lo, s20, 0x80
	s_addc_u32 vcc_hi, s21, 0
	global_load_lds_dwordx4 v150, vcc
	s_waitcnt vmcnt(8)
	s_waitcnt lgkmcnt(0)
	s_setprio 1
	s_barrier
	v_mfma_f32_16x16x32_bf16 v[64:67], v[132:135], v[204:207], v[64:67]
	v_mfma_f32_16x16x32_bf16 v[60:63], v[158:161], v[204:207], v[60:63]
	v_mfma_f32_16x16x32_bf16 v[48:51], v[132:135], v[212:215], v[48:51]
	v_mfma_f32_16x16x32_bf16 v[44:47], v[158:161], v[212:215], v[44:47]
	v_mfma_f32_16x16x32_bf16 v[32:35], v[132:135], v[220:223], v[32:35]
	v_mfma_f32_16x16x32_bf16 v[28:31], v[158:161], v[220:223], v[28:31]
	v_mfma_f32_16x16x32_bf16 v[16:19], v[132:135], v[228:231], v[16:19]
	v_mfma_f32_16x16x32_bf16 v[12:15], v[158:161], v[228:231], v[12:15]
	v_mfma_f32_16x16x32_bf16 v[64:67], v[136:139], v[208:211], v[64:67]
	v_mfma_f32_16x16x32_bf16 v[60:63], v[162:165], v[208:211], v[60:63]
	v_mfma_f32_16x16x32_bf16 v[48:51], v[136:139], v[216:219], v[48:51]
	v_mfma_f32_16x16x32_bf16 v[44:47], v[162:165], v[216:219], v[44:47]
	v_mfma_f32_16x16x32_bf16 v[32:35], v[136:139], v[224:227], v[32:35]
	v_mfma_f32_16x16x32_bf16 v[28:31], v[162:165], v[224:227], v[28:31]
	v_mfma_f32_16x16x32_bf16 v[16:19], v[136:139], v[232:235], v[16:19]
	v_mfma_f32_16x16x32_bf16 v[12:15], v[162:165], v[232:235], v[12:15]
	v_mfma_f32_16x16x32_bf16 v[56:59], v[188:191], v[204:207], v[56:59]
	v_mfma_f32_16x16x32_bf16 v[52:55], v[196:199], v[204:207], v[52:55]
	v_mfma_f32_16x16x32_bf16 v[40:43], v[188:191], v[212:215], v[40:43]
	v_mfma_f32_16x16x32_bf16 v[36:39], v[196:199], v[212:215], v[36:39]
	v_mfma_f32_16x16x32_bf16 v[24:27], v[188:191], v[220:223], v[24:27]
	v_mfma_f32_16x16x32_bf16 v[20:23], v[196:199], v[220:223], v[20:23]
	v_mfma_f32_16x16x32_bf16 v[8:11], v[188:191], v[228:231], v[8:11]
	v_mfma_f32_16x16x32_bf16 v[4:7], v[196:199], v[228:231], v[4:7]
	v_mfma_f32_16x16x32_bf16 v[56:59], v[192:195], v[208:211], v[56:59]
	v_mfma_f32_16x16x32_bf16 v[52:55], v[200:203], v[208:211], v[52:55]
	v_mfma_f32_16x16x32_bf16 v[40:43], v[192:195], v[216:219], v[40:43]
	v_mfma_f32_16x16x32_bf16 v[36:39], v[200:203], v[216:219], v[36:39]
	v_mfma_f32_16x16x32_bf16 v[24:27], v[192:195], v[224:227], v[24:27]
	v_mfma_f32_16x16x32_bf16 v[20:23], v[200:203], v[224:227], v[20:23]
	v_mfma_f32_16x16x32_bf16 v[8:11], v[192:195], v[232:235], v[8:11]
	v_mfma_f32_16x16x32_bf16 v[4:7], v[200:203], v[232:235], v[4:7]
	s_barrier
	s_setprio 0
	s_add_i32 s57, s57, 2
	s_add_u32 s51, s51, 0x100
	s_addc_u32 s56, s56, 0
	s_cmpk_gt_u32 s57, 0x55
	s_mov_b64 s[14:15], s[16:17]
	s_cbranch_scc0 .LBB0_167
	s_and_b64 vcc, exec, s[10:11]
	s_cbranch_vccz .LBB0_170
	s_barrier

; #define PG8_STAGE(bufoff, gbase, voff) do { _Pragma("unroll") for (int _i = 0; _i < 2; ++_i) \
;         __builtin_amdgcn_global_load_lds((const unsigned*)((const char*)(gbase) + (voff)[_i]), (PG8_LAS unsigned*)(lds + (bufoff) + ldsw + _i * 8192), 16, 0, 0); } while (0)
; #define PG8_WAIT_V(n) asm volatile("s_waitcnt vmcnt(" #n ")" ::: "memory")
; #define PG8_BAR __builtin_amdgcn_s_barrier()
; template <class Epi, class Sched, bool ALIGN_EPI = false, bool SP2 = false>
; __device__ __forceinline__ void gemm_phase(PG8_LAS unsigned char* lds, const Gemm g, const Sched& S, const Epi& E) {
;     ...
;     for (int i = 0; i < 2; ++i) { int R, C; stage_rc(tid * 16 + i * 8192, R, C); const int Rb = Epi::PERM ? ((R & ~31) + perm32(R & 31)) : R;
;         voffA[i] = (unsigned)(R * K + C) * 2u; voffB[i] = (unsigned)(Rb * K + C) * 2u; }
;     const size_t kstep = (size_t)(BK * 2);
;     const size_t hstep = (size_t)HALF * K * 2;
;     const size_t tstep = 2 * hstep;
;     const unsigned ldsw = (unsigned)wid * 1024u;
;     const int aoff = lds_byte(wr * 64 + fr, fq * 8), boff = lds_byte(wc * 32 + fr, fq * 8);
;     ...
;     if constexpr (SP2) {
;         PG8_STAGE(PG8_SB(0, 0), cB, voffB); PG8_STAGE(PG8_SB(0, 1), cB + hstep, voffB); PG8_STAGE(PG8_SA(0, 0), cA, voffA); PG8_STAGE(PG8_SA(0, 1), cA + hstep, voffA);
;         if (wr == 1) PG8_BAR;
;         PG8_WAIT_V(2); PG8_BAR;
;         PG8_STAGE(PG8_SB(1, 0), cB + kstep, voffB); PG8_STAGE(PG8_SA(1, 0), cA + kstep, voffA); PG8_STAGE(PG8_SB(1, 1), cB + hstep + kstep, voffB);
;         PG8_WAIT_V(6); PG8_BAR;
.LBB0_561:
	v_lshrrev_b32_e32 v19, 1, v19
	v_or_b32_e32 v152, s8, v18
	v_and_b32_e32 v19, 24, v19
	s_sext_i32_i16 s17, s2
	v_lshlrev_b32_e32 v20, 6, v152
	v_lshlrev_b32_e32 v21, 1, v19
	s_movk_i32 s2, 0x3c0
	v_lshlrev_b32_e32 v22, 2, v152
	v_and_or_b32 v20, v20, s2, v21
	s_lshl_b32 s2, s7, 13
	v_and_b32_e32 v22, 32, v22
	v_bitop3_b32 v20, v20, s2, v22 bitop3:0xde
	s_lshl_b32 s2, s6, 5
	s_and_b32 s2, s2, 0x60
	v_lshl_or_b32 v21, v18, 6, v21
	v_lshlrev_b32_e32 v18, 2, v18
	s_add_i32 m0, s29, 0x18000
	v_lshl_add_u64 v[10:11], v[10:11], 0, s[36:37]
	s_lshl_b32 s6, s2, 7
	v_and_b32_e32 v18, 32, v18
	s_waitcnt vmcnt(2)
	s_barrier
	global_load_lds_dwordx4 v[10:11], off
	v_lshl_add_u64 v[8:9], v[8:9], 0, s[36:37]
	s_add_i32 m0, s29, 0x1a000
	s_add_i32 s35, s29, 0x8000
	s_add_i32 s42, s29, 0xa000
	v_bitop3_b32 v153, v21, s6, v18 bitop3:0xde
	global_load_lds_dwordx4 v[8:9], off
	v_lshl_add_u64 v[4:5], v[4:5], 0, s[36:37]
	s_mov_b32 m0, s35
	s_add_u32 s6, s20, 0x80080
	global_load_lds_dwordx4 v[4:5], off
	v_lshl_add_u64 v[4:5], v[6:7], 0, s[36:37]
	s_mov_b32 m0, s42
	s_addc_u32 s7, s21, 0
	global_load_lds_dwordx4 v[4:5], off
	s_add_i32 m0, s29, 0x1c000
	v_lshl_add_u64 v[4:5], s[6:7], 0, v[2:3]
	global_load_lds_dwordx4 v[4:5], off
	v_lshl_add_u64 v[4:5], s[6:7], 0, v[0:1]
	s_add_i32 m0, s29, 0x1e000
	s_cmpk_lt_u32 s3, 0x100
	global_load_lds_dwordx4 v[4:5], off
	v_lshlrev_b32_e32 v4, 15, v16
	v_and_b32_e32 v4, 0xffff0000, v4
	v_lshl_add_u32 v4, v15, 12, v4
	v_and_b32_e32 v5, 1, v16
	v_lshl_or_b32 v4, v5, 6, v4
	v_lshl_add_u32 v136, v17, 1, v4
	v_lshlrev_b32_e32 v4, 15, v12
	v_and_b32_e32 v4, 0xffff0000, v4
	s_waitcnt vmcnt(6)
	v_lshl_add_u32 v4, v13, 12, v4
	v_and_b32_e32 v5, 1, v12
	v_lshl_or_b32 v4, v5, 6, v4
	s_cselect_b64 s[6:7], -1, 0
	v_or_b32_e32 v154, s2, v19
	v_mov_b32_e32 v137, v3
	v_lshl_add_u32 v138, v14, 1, v4
	v_mov_b32_e32 v139, v3
	s_mov_b32 s44, 0
	v_add_u32_e32 v155, 0, v20
	s_barrier
	v_add_u32_e32 v166, 0x10000, v153
	ds_read_b128 v[184:187], v166
	ds_read_b128 v[188:191], v166 offset:1024
	ds_read_b128 v[192:195], v166 offset:2048
	ds_read_b128 v[196:199], v166 offset:3072
	v_add_u32_e32 v167, 0x14000, v153
	ds_read_b128 v[200:203], v167
	ds_read_b128 v[204:207], v167 offset:1024
	ds_read_b128 v[208:211], v167 offset:2048
	ds_read_b128 v[212:215], v167 offset:3072
	ds_read_b128 v[216:219], v155
	ds_read_b128 v[220:223], v155 offset:1024
	ds_read_b128 v[224:227], v155 offset:2048
	ds_read_b128 v[228:231], v155 offset:3072
	ds_read_b128 v[232:235], v155 offset:4096
	ds_read_b128 v[236:239], v155 offset:5120
	ds_read_b128 v[240:243], v155 offset:6144
	ds_read_b128 v[244:247], v155 offset:7168
	s_branch .LBB0_564

; #define PG8_STAGE(bufoff, gbase, voff) do { _Pragma("unroll") for (int _i = 0; _i < 2; ++_i) \
;         __builtin_amdgcn_global_load_lds((const unsigned*)((const char*)(gbase) + (voff)[_i]), (PG8_LAS unsigned*)(lds + (bufoff) + ldsw + _i * 8192), 16, 0, 0); } while (0)
; #define PG8_LDA(dst, b, h) do { _Pragma("unroll") for (int m = 0; m < 4; ++m) _Pragma("unroll") for (int k = 0; k < 2; ++k) dst[m][k] = *(const PG8_LAS bf16x8*)(lds + PG8_SA(b, h) + aoff + m * 2048 + k * 1024); } while (0)
; #define PG8_LDB(dst, b, h) do { _Pragma("unroll") for (int n = 0; n < 2; ++n) _Pragma("unroll") for (int k = 0; k < 2; ++k) dst[n][k] = *(const PG8_LAS bf16x8*)(lds + PG8_SB(b, h) + boff + n * 2048 + k * 1024); } while (0)
; #define PG8_WAIT_V(n) asm volatile("s_waitcnt vmcnt(" #n ")" ::: "memory")
; #define PG8_WAIT_L(n) asm volatile("s_waitcnt lgkmcnt(" #n ")" ::: "memory")
; #define PG8_BAR __builtin_amdgcn_s_barrier()
; #define PG8_SCHED __builtin_amdgcn_sched_barrier(0)
; template <class Epi, class Sched, bool ALIGN_EPI = false, bool SP2 = false>
; __device__ __forceinline__ void gemm_phase(PG8_LAS unsigned char* lds, const Gemm g, const Sched& S, const Epi& E) {
;     ...
;         const char* nA = has_next ? (const char*)g.A + (size_t)nxt.pm * tstep : cA; const char* nB = has_next ? (const char*)g.Bt + (size_t)nxt.pn * tstep : cB;
;         for (int t = 0; t < nt; t += 2) {
;             const bool last = (t == nt - 2);
;             const char* a1 = cA + (size_t)(t + 1) * kstep;
;             const char* a2 = last ? nA : cA + (size_t)(t + 2) * kstep; const char* b2 = last ? nB : cB + (size_t)(t + 2) * kstep;
;             const char* a3 = a2 + kstep; const char* b3 = b2 + kstep;
;             if (last && has_next) S.a_ready(nxt);
;             if constexpr (SP2) {
;             PG8_LDB(B0, 0, 0); PG8_LDB(B1, 0, 1); PG8_SCHED; PG8_LDA(At, 0, 0); PG8_STAGE(PG8_SA(1, 1), a1 + hstep, voffA);
;             PG8_WAIT_V(8); PG8_WAIT_L(0); PG8_BAR; PG8_MMA(0, 0, At, B0); PG8_MMA(0, 1, At, B1); PG8_BAR; PG8_SCHED;
;             PG8_LDA(At, 0, 1); PG8_STAGE(PG8_SB(0, 0), b2, voffB); PG8_STAGE(PG8_SB(0, 1), b2 + hstep, voffB); PG8_STAGE(PG8_SA(0, 0), a2, voffA);
;             PG8_WAIT_V(8); PG8_WAIT_L(0); PG8_BAR; PG8_MMA(1, 0, At, B0); PG8_MMA(1, 1, At, B1); PG8_BAR; PG8_SCHED;
.LBB0_566:
	s_ashr_i32 s11, s10, 31
	s_lshl_b64 s[12:13], s[10:11], 20
	s_add_u32 s12, s46, s12
	s_addc_u32 s13, s47, s13
	s_and_b64 s[14:15], s[2:3], exec
	s_cselect_b32 s11, s13, s19
	s_cselect_b32 s45, s12, s18
	s_ashr_i32 s9, s8, 31
	s_lshl_b64 s[14:15], s[8:9], 20
	s_add_u32 s14, s25, s14
	s_addc_u32 s15, s26, s15
	s_and_b64 s[22:23], s[2:3], exec
	s_cselect_b32 s9, s15, s21
	s_cselect_b32 s50, s14, s20
	s_add_u32 s18, s18, 0x80080
	s_addc_u32 s19, s19, 0
	s_add_u32 s51, s20, 0x100
	s_addc_u32 s56, s21, 0
	s_mov_b32 s57, -2
	s_add_u32 s20, s18, 0xfff80080
	s_addc_u32 s21, s19, -1
	s_add_i32 s63, 0, 0x10000
	s_cmp_eq_u32 s57, 28
	s_cselect_b32 s23, s11, s21
	s_cselect_b32 s22, s45, s20
	s_cselect_b32 s21, s9, s56
	s_cselect_b32 s20, s50, s51
	s_add_i32 s66, 0, 0x14000
	s_add_i32 m0, s29, 0xc000
	s_nop 0
	global_load_lds_dwordx4 v136, s[18:19]
	s_add_i32 m0, s29, 0xe000
	s_nop 0
	global_load_lds_dwordx4 v138, s[18:19]
	s_waitcnt vmcnt(8)
	s_waitcnt lgkmcnt(0)
	s_setprio 1
	s_barrier
	v_mfma_f32_16x16x32_bf16 v[128:131], v[184:187], v[216:219], 0
	v_mfma_f32_16x16x32_bf16 v[120:123], v[192:195], v[216:219], 0
	v_mfma_f32_16x16x32_bf16 v[112:115], v[184:187], v[224:227], 0
	v_mfma_f32_16x16x32_bf16 v[104:107], v[192:195], v[224:227], 0
	v_mfma_f32_16x16x32_bf16 v[96:99], v[184:187], v[232:235], 0
	v_mfma_f32_16x16x32_bf16 v[88:91], v[192:195], v[232:235], 0
	v_mfma_f32_16x16x32_bf16 v[80:83], v[184:187], v[240:243], 0
	v_mfma_f32_16x16x32_bf16 v[72:75], v[192:195], v[240:243], 0
	v_mfma_f32_16x16x32_bf16 v[128:131], v[188:191], v[220:223], v[128:131]
	v_mfma_f32_16x16x32_bf16 v[120:123], v[196:199], v[220:223], v[120:123]
	v_mfma_f32_16x16x32_bf16 v[112:115], v[188:191], v[228:231], v[112:115]
	v_mfma_f32_16x16x32_bf16 v[104:107], v[196:199], v[228:231], v[104:107]
	v_mfma_f32_16x16x32_bf16 v[96:99], v[188:191], v[236:239], v[96:99]
	v_mfma_f32_16x16x32_bf16 v[88:91], v[196:199], v[236:239], v[88:91]
	v_mfma_f32_16x16x32_bf16 v[80:83], v[188:191], v[244:247], v[80:83]
	v_mfma_f32_16x16x32_bf16 v[72:75], v[196:199], v[244:247], v[72:75]
	v_mfma_f32_16x16x32_bf16 v[124:127], v[200:203], v[216:219], 0
	v_mfma_f32_16x16x32_bf16 v[116:119], v[208:211], v[216:219], 0
	v_mfma_f32_16x16x32_bf16 v[108:111], v[200:203], v[224:227], 0
	v_mfma_f32_16x16x32_bf16 v[100:103], v[208:211], v[224:227], 0
	v_mfma_f32_16x16x32_bf16 v[92:95], v[200:203], v[232:235], 0
	v_mfma_f32_16x16x32_bf16 v[84:87], v[208:211], v[232:235], 0
	v_mfma_f32_16x16x32_bf16 v[76:79], v[200:203], v[240:243], 0
	v_mfma_f32_16x16x32_bf16 v[68:71], v[208:211], v[240:243], 0
	v_mfma_f32_16x16x32_bf16 v[124:127], v[204:207], v[220:223], v[124:127]
	v_mfma_f32_16x16x32_bf16 v[116:119], v[212:215], v[220:223], v[116:119]
	v_mfma_f32_16x16x32_bf16 v[108:111], v[204:207], v[228:231], v[108:111]
	v_mfma_f32_16x16x32_bf16 v[100:103], v[212:215], v[228:231], v[100:103]
	v_mfma_f32_16x16x32_bf16 v[92:95], v[204:207], v[236:239], v[92:95]
	v_mfma_f32_16x16x32_bf16 v[84:87], v[212:215], v[236:239], v[84:87]
	v_mfma_f32_16x16x32_bf16 v[76:79], v[204:207], v[244:247], v[76:79]
	v_mfma_f32_16x16x32_bf16 v[68:71], v[212:215], v[244:247], v[68:71]
	s_barrier
	s_setprio 0
	s_add_i32 s63, s63, s27
	s_mov_b32 m0, s63
	ds_read_b128 v[216:219], v155 offset:16384
	ds_read_b128 v[220:223], v155 offset:17408
	ds_read_b128 v[224:227], v155 offset:18432
	ds_read_b128 v[228:231], v155 offset:19456
	ds_read_b128 v[232:235], v155 offset:20480
	ds_read_b128 v[236:239], v155 offset:21504
	ds_read_b128 v[240:243], v155 offset:22528
	ds_read_b128 v[244:247], v155 offset:23552
	global_load_lds_dwordx4 v2, s[20:21]
	s_add_i32 m0, s63, 0x2000
	s_add_u32 s64, s20, 0x80000
	s_addc_u32 s65, s21, 0
	s_add_i32 s63, s66, s27
	global_load_lds_dwordx4 v0, s[20:21]
	s_mov_b32 m0, s63
	v_lshl_add_u64 v[250:251], s[22:23], 0, v[132:133]
	global_load_lds_dwordx4 v2, s[64:65]
	s_add_i32 m0, s63, 0x2000
	s_nop 0
	global_load_lds_dwordx4 v0, s[64:65]
	v_lshl_add_u64 v[248:249], s[22:23], 0, v[134:135]
	s_mov_b32 m0, s29
	s_nop 0
	global_load_lds_dwordx4 v[248:249], off
	s_mov_b32 m0, s30
	s_nop 0
	global_load_lds_dwordx4 v[250:251], off
	s_waitcnt vmcnt(8)
	s_waitcnt lgkmcnt(0)
	s_setprio 1
	s_barrier
	v_mfma_f32_16x16x32_bf16 v[64:67], v[184:187], v[216:219], 0
	v_mfma_f32_16x16x32_bf16 v[56:59], v[192:195], v[216:219], 0
	v_mfma_f32_16x16x32_bf16 v[48:51], v[184:187], v[224:227], 0
	v_mfma_f32_16x16x32_bf16 v[40:43], v[192:195], v[224:227], 0
	v_mfma_f32_16x16x32_bf16 v[32:35], v[184:187], v[232:235], 0
	v_mfma_f32_16x16x32_bf16 v[24:27], v[192:195], v[232:235], 0
	v_mfma_f32_16x16x32_bf16 v[16:19], v[184:187], v[240:243], 0
	v_mfma_f32_16x16x32_bf16 v[8:11], v[192:195], v[240:243], 0
	v_mfma_f32_16x16x32_bf16 v[64:67], v[188:191], v[220:223], v[64:67]
	v_mfma_f32_16x16x32_bf16 v[56:59], v[196:199], v[220:223], v[56:59]
	v_mfma_f32_16x16x32_bf16 v[48:51], v[188:191], v[228:231], v[48:51]
	v_mfma_f32_16x16x32_bf16 v[40:43], v[196:199], v[228:231], v[40:43]
	v_mfma_f32_16x16x32_bf16 v[32:35], v[188:191], v[236:239], v[32:35]
	v_mfma_f32_16x16x32_bf16 v[24:27], v[196:199], v[236:239], v[24:27]
	v_mfma_f32_16x16x32_bf16 v[16:19], v[188:191], v[244:247], v[16:19]
	v_mfma_f32_16x16x32_bf16 v[8:11], v[196:199], v[244:247], v[8:11]
	v_mfma_f32_16x16x32_bf16 v[60:63], v[200:203], v[216:219], 0
	v_mfma_f32_16x16x32_bf16 v[52:55], v[208:211], v[216:219], 0
	v_mfma_f32_16x16x32_bf16 v[44:47], v[200:203], v[224:227], 0
	v_mfma_f32_16x16x32_bf16 v[36:39], v[208:211], v[224:227], 0
	v_mfma_f32_16x16x32_bf16 v[28:31], v[200:203], v[232:235], 0
	v_mfma_f32_16x16x32_bf16 v[20:23], v[208:211], v[232:235], 0
	v_mfma_f32_16x16x32_bf16 v[12:15], v[200:203], v[240:243], 0
	v_mfma_f32_16x16x32_bf16 v[4:7], v[208:211], v[240:243], 0
	v_mfma_f32_16x16x32_bf16 v[60:63], v[204:207], v[220:223], v[60:63]
	v_mfma_f32_16x16x32_bf16 v[52:55], v[212:215], v[220:223], v[52:55]
	v_mfma_f32_16x16x32_bf16 v[44:47], v[204:207], v[228:231], v[44:47]
	v_mfma_f32_16x16x32_bf16 v[36:39], v[212:215], v[228:231], v[36:39]
	v_mfma_f32_16x16x32_bf16 v[28:31], v[204:207], v[236:239], v[28:31]
	v_mfma_f32_16x16x32_bf16 v[20:23], v[212:215], v[236:239], v[20:23]
	v_mfma_f32_16x16x32_bf16 v[12:15], v[204:207], v[244:247], v[12:15]
	v_mfma_f32_16x16x32_bf16 v[4:7], v[212:215], v[244:247], v[4:7]
	s_barrier
; #define PG8_STAGE(bufoff, gbase, voff) do { _Pragma("unroll") for (int _i = 0; _i < 2; ++_i) \
;         __builtin_amdgcn_global_load_lds((const unsigned*)((const char*)(gbase) + (voff)[_i]), (PG8_LAS unsigned*)(lds + (bufoff) + ldsw + _i * 8192), 16, 0, 0); } while (0)
; #define PG8_LDA(dst, b, h) do { _Pragma("unroll") for (int m = 0; m < 4; ++m) _Pragma("unroll") for (int k = 0; k < 2; ++k) dst[m][k] = *(const PG8_LAS bf16x8*)(lds + PG8_SA(b, h) + aoff + m * 2048 + k * 1024); } while (0)
; #define PG8_LDB(dst, b, h) do { _Pragma("unroll") for (int n = 0; n < 2; ++n) _Pragma("unroll") for (int k = 0; k < 2; ++k) dst[n][k] = *(const PG8_LAS bf16x8*)(lds + PG8_SB(b, h) + boff + n * 2048 + k * 1024); } while (0)
; #define PG8_MMA(ai, bj, At, Bt) do { __builtin_amdgcn_s_setprio(1); _Pragma("unroll") for (int m = 0; m < 4; ++m) _Pragma("unroll") for (int n = 0; n < 2; ++n) _Pragma("unroll") for (int k = 0; k < 2; ++k) \
;         acc[ai][bj][m][n] = __builtin_amdgcn_mfma_f32_16x16x32_bf16(Bt[n][k], At[m][k], acc[ai][bj][m][n], 0, 0, 0); __builtin_amdgcn_s_setprio(0); } while (0)
; #define PG8_WAIT_V(n) asm volatile("s_waitcnt vmcnt(" #n ")" ::: "memory")
; #define PG8_WAIT_L(n) asm volatile("s_waitcnt lgkmcnt(" #n ")" ::: "memory")
; #define PG8_BAR __builtin_amdgcn_s_barrier()
; #define PG8_SCHED __builtin_amdgcn_sched_barrier(0)
; template <class Epi, class Sched, bool ALIGN_EPI = false, bool SP2 = false>
; __device__ __forceinline__ void gemm_phase(PG8_LAS unsigned char* lds, const Gemm g, const Sched& S, const Epi& E) {
;     ...
;             PG8_LDB(B0, 1, 0); PG8_LDB(B1, 1, 1); PG8_SCHED; PG8_LDA(At, 1, 0); PG8_STAGE(PG8_SA(0, 1), a2 + hstep, voffA);
;             PG8_WAIT_V(8); PG8_WAIT_L(0); PG8_BAR; PG8_MMA(0, 0, At, B0); PG8_MMA(0, 1, At, B1); PG8_BAR; PG8_SCHED;
;             PG8_LDA(At, 1, 1); PG8_STAGE(PG8_SB(1, 0), b3, voffB); PG8_STAGE(PG8_SB(1, 1), b3 + hstep, voffB); PG8_STAGE(PG8_SA(1, 0), a3, voffA);
;             PG8_WAIT_V(8); PG8_WAIT_L(0); PG8_BAR; PG8_MMA(1, 0, At, B0); PG8_MMA(1, 1, At, B1); PG8_BAR; PG8_SCHED;
	s_setprio 0
	s_add_i32 s63, 0, 0x18000
	v_add_u32_e32 v161, s63, v153
	s_add_i32 s64, 0, 0x1c000
	ds_read_b128 v[184:187], v161
	ds_read_b128 v[188:191], v161 offset:1024
	ds_read_b128 v[192:195], v161 offset:2048
	ds_read_b128 v[196:199], v161 offset:3072
	v_add_u32_e32 v161, s64, v153
	ds_read_b128 v[200:203], v161
	ds_read_b128 v[204:207], v161 offset:1024
	ds_read_b128 v[208:211], v161 offset:2048
	ds_read_b128 v[212:215], v161 offset:3072
	s_add_u32 s22, s22, 0x80000
	s_addc_u32 s23, s23, 0
	s_mov_b32 m0, s31
	ds_read_b128 v[216:219], v155 offset:32768
	ds_read_b128 v[220:223], v155 offset:33792
	ds_read_b128 v[224:227], v155 offset:34816
	ds_read_b128 v[228:231], v155 offset:35840
	ds_read_b128 v[232:235], v155 offset:36864
	ds_read_b128 v[236:239], v155 offset:37888
	ds_read_b128 v[240:243], v155 offset:38912
	ds_read_b128 v[244:247], v155 offset:39936
	global_load_lds_dwordx4 v134, s[22:23]
	s_mov_b32 m0, s34
	s_nop 0
	global_load_lds_dwordx4 v132, s[22:23]
	s_waitcnt vmcnt(8)
	s_waitcnt lgkmcnt(0)
	s_setprio 1
	s_barrier
	v_mfma_f32_16x16x32_bf16 v[128:131], v[184:187], v[216:219], v[128:131]
	v_mfma_f32_16x16x32_bf16 v[120:123], v[192:195], v[216:219], v[120:123]
	v_mfma_f32_16x16x32_bf16 v[112:115], v[184:187], v[224:227], v[112:115]
	v_mfma_f32_16x16x32_bf16 v[104:107], v[192:195], v[224:227], v[104:107]
	v_mfma_f32_16x16x32_bf16 v[96:99], v[184:187], v[232:235], v[96:99]
	v_mfma_f32_16x16x32_bf16 v[88:91], v[192:195], v[232:235], v[88:91]
	v_mfma_f32_16x16x32_bf16 v[80:83], v[184:187], v[240:243], v[80:83]
	v_mfma_f32_16x16x32_bf16 v[72:75], v[192:195], v[240:243], v[72:75]
	v_mfma_f32_16x16x32_bf16 v[128:131], v[188:191], v[220:223], v[128:131]
	v_mfma_f32_16x16x32_bf16 v[120:123], v[196:199], v[220:223], v[120:123]
	v_mfma_f32_16x16x32_bf16 v[112:115], v[188:191], v[228:231], v[112:115]
	v_mfma_f32_16x16x32_bf16 v[104:107], v[196:199], v[228:231], v[104:107]
	v_mfma_f32_16x16x32_bf16 v[96:99], v[188:191], v[236:239], v[96:99]
	v_mfma_f32_16x16x32_bf16 v[88:91], v[196:199], v[236:239], v[88:91]
	v_mfma_f32_16x16x32_bf16 v[80:83], v[188:191], v[244:247], v[80:83]
	v_mfma_f32_16x16x32_bf16 v[72:75], v[196:199], v[244:247], v[72:75]
	v_mfma_f32_16x16x32_bf16 v[124:127], v[200:203], v[216:219], v[124:127]
	v_mfma_f32_16x16x32_bf16 v[116:119], v[208:211], v[216:219], v[116:119]
	v_mfma_f32_16x16x32_bf16 v[108:111], v[200:203], v[224:227], v[108:111]
	v_mfma_f32_16x16x32_bf16 v[100:103], v[208:211], v[224:227], v[100:103]
	v_mfma_f32_16x16x32_bf16 v[92:95], v[200:203], v[232:235], v[92:95]
	v_mfma_f32_16x16x32_bf16 v[84:87], v[208:211], v[232:235], v[84:87]
	v_mfma_f32_16x16x32_bf16 v[76:79], v[200:203], v[240:243], v[76:79]
	v_mfma_f32_16x16x32_bf16 v[68:71], v[208:211], v[240:243], v[68:71]
	v_mfma_f32_16x16x32_bf16 v[124:127], v[204:207], v[220:223], v[124:127]
	v_mfma_f32_16x16x32_bf16 v[116:119], v[212:215], v[220:223], v[116:119]
	v_mfma_f32_16x16x32_bf16 v[108:111], v[204:207], v[228:231], v[108:111]
	v_mfma_f32_16x16x32_bf16 v[100:103], v[212:215], v[228:231], v[100:103]
	v_mfma_f32_16x16x32_bf16 v[92:95], v[204:207], v[236:239], v[92:95]
	v_mfma_f32_16x16x32_bf16 v[84:87], v[212:215], v[236:239], v[84:87]
	v_mfma_f32_16x16x32_bf16 v[76:79], v[204:207], v[244:247], v[76:79]
	v_mfma_f32_16x16x32_bf16 v[68:71], v[212:215], v[244:247], v[68:71]
	s_barrier
	s_setprio 0
	s_add_i32 s22, s63, s27
	s_mov_b32 m0, s22
	ds_read_b128 v[216:219], v155 offset:49152
	ds_read_b128 v[220:223], v155 offset:50176
	ds_read_b128 v[224:227], v155 offset:51200
	ds_read_b128 v[228:231], v155 offset:52224
	ds_read_b128 v[232:235], v155 offset:53248
	ds_read_b128 v[236:239], v155 offset:54272
	ds_read_b128 v[240:243], v155 offset:55296
	ds_read_b128 v[244:247], v155 offset:56320
	s_add_u32 vcc_lo, s20, 0x80
	s_addc_u32 vcc_hi, s21, 0
	global_load_lds_dwordx4 v2, vcc
	s_add_i32 m0, s22, 0x2000
	s_add_u32 s20, s20, 0x80080
	s_addc_u32 s21, s21, 0
	s_add_i32 s22, s64, s27
	s_add_u32 vcc_lo, s20, 0xfff80000
	s_addc_u32 vcc_hi, s21, -1
	global_load_lds_dwordx4 v0, vcc
	s_mov_b32 m0, s22
	s_nop 0
	global_load_lds_dwordx4 v2, s[20:21]
	s_add_i32 m0, s22, 0x2000
	s_nop 0
	global_load_lds_dwordx4 v0, s[20:21]
	v_lshl_add_u64 v[150:151], v[248:249], 0, s[36:37]
	s_mov_b32 m0, s35
	s_nop 0
	global_load_lds_dwordx4 v[150:151], off
	v_lshl_add_u64 v[150:151], v[250:251], 0, s[36:37]
	s_mov_b32 m0, s42
	s_nop 0
	global_load_lds_dwordx4 v[150:151], off
	s_waitcnt vmcnt(8)
	s_waitcnt lgkmcnt(0)
	s_setprio 1
	s_barrier
	v_mfma_f32_16x16x32_bf16 v[64:67], v[184:187], v[216:219], v[64:67]
	v_mfma_f32_16x16x32_bf16 v[56:59], v[192:195], v[216:219], v[56:59]
	v_mfma_f32_16x16x32_bf16 v[48:51], v[184:187], v[224:227], v[48:51]
	v_mfma_f32_16x16x32_bf16 v[40:43], v[192:195], v[224:227], v[40:43]
	v_mfma_f32_16x16x32_bf16 v[32:35], v[184:187], v[232:235], v[32:35]
	v_mfma_f32_16x16x32_bf16 v[24:27], v[192:195], v[232:235], v[24:27]
	v_mfma_f32_16x16x32_bf16 v[16:19], v[184:187], v[240:243], v[16:19]
	v_mfma_f32_16x16x32_bf16 v[8:11], v[192:195], v[240:243], v[8:11]
	v_mfma_f32_16x16x32_bf16 v[64:67], v[188:191], v[220:223], v[64:67]
	v_mfma_f32_16x16x32_bf16 v[56:59], v[196:199], v[220:223], v[56:59]
	v_mfma_f32_16x16x32_bf16 v[48:51], v[188:191], v[228:231], v[48:51]
	v_mfma_f32_16x16x32_bf16 v[40:43], v[196:199], v[228:231], v[40:43]
	v_mfma_f32_16x16x32_bf16 v[32:35], v[188:191], v[236:239], v[32:35]
	v_mfma_f32_16x16x32_bf16 v[24:27], v[196:199], v[236:239], v[24:27]
	v_mfma_f32_16x16x32_bf16 v[16:19], v[188:191], v[244:247], v[16:19]
	v_mfma_f32_16x16x32_bf16 v[8:11], v[196:199], v[244:247], v[8:11]
	v_mfma_f32_16x16x32_bf16 v[60:63], v[200:203], v[216:219], v[60:63]
	v_mfma_f32_16x16x32_bf16 v[52:55], v[208:211], v[216:219], v[52:55]
	v_mfma_f32_16x16x32_bf16 v[44:47], v[200:203], v[224:227], v[44:47]
	v_mfma_f32_16x16x32_bf16 v[36:39], v[208:211], v[224:227], v[36:39]
	v_mfma_f32_16x16x32_bf16 v[28:31], v[200:203], v[232:235], v[28:31]
	v_mfma_f32_16x16x32_bf16 v[20:23], v[208:211], v[232:235], v[20:23]
	v_mfma_f32_16x16x32_bf16 v[12:15], v[200:203], v[240:243], v[12:15]
	v_mfma_f32_16x16x32_bf16 v[4:7], v[208:211], v[240:243], v[4:7]
	v_mfma_f32_16x16x32_bf16 v[60:63], v[204:207], v[220:223], v[60:63]
	v_mfma_f32_16x16x32_bf16 v[52:55], v[212:215], v[220:223], v[52:55]
	v_mfma_f32_16x16x32_bf16 v[44:47], v[204:207], v[228:231], v[44:47]
	v_mfma_f32_16x16x32_bf16 v[36:39], v[212:215], v[228:231], v[36:39]
	v_mfma_f32_16x16x32_bf16 v[28:31], v[204:207], v[236:239], v[28:31]
	v_mfma_f32_16x16x32_bf16 v[20:23], v[212:215], v[236:239], v[20:23]
	v_mfma_f32_16x16x32_bf16 v[12:15], v[204:207], v[244:247], v[12:15]
	v_mfma_f32_16x16x32_bf16 v[4:7], v[212:215], v[244:247], v[4:7]
	s_barrier
	s_setprio 0
	s_add_i32 s57, s57, 2
	s_add_u32 s18, s18, 0x100
	s_addc_u32 s19, s19, 0
	s_add_u32 s51, s51, 0x100
	s_addc_u32 s56, s56, 0
	s_cmp_gt_u32 s57, 29

; __device__ __forceinline__ unsigned cvt_pk_bf16(float lo, float hi) { unsigned r; asm volatile("v_cvt_pk_bf16_f32 %0, %1, %2" : "=v"(r) : "v"(lo), "v"(hi)); return r; }
; #define PG8_STAGE(bufoff, gbase, voff) do { _Pragma("unroll") for (int _i = 0; _i < 2; ++_i) \
;         __builtin_amdgcn_global_load_lds((const unsigned*)((const char*)(gbase) + (voff)[_i]), (PG8_LAS unsigned*)(lds + (bufoff) + ldsw + _i * 8192), 16, 0, 0); } while (0)
; #define PG8_LDA(dst, b, h) do { _Pragma("unroll") for (int m = 0; m < 4; ++m) _Pragma("unroll") for (int k = 0; k < 2; ++k) dst[m][k] = *(const PG8_LAS bf16x8*)(lds + PG8_SA(b, h) + aoff + m * 2048 + k * 1024); } while (0)
; #define PG8_LDB(dst, b, h) do { _Pragma("unroll") for (int n = 0; n < 2; ++n) _Pragma("unroll") for (int k = 0; k < 2; ++k) dst[n][k] = *(const PG8_LAS bf16x8*)(lds + PG8_SB(b, h) + boff + n * 2048 + k * 1024); } while (0)
; #define PG8_SCHED __builtin_amdgcn_sched_barrier(0)
;     __device__ __forceinline__ void operator()(const f32x4 (&acc)[2][2][4][2], const Unit& u, int wr, int wc, int fr, int fq, const float (&pf)[8]) const {
;         const int row0 = u.pm * BM + wr * 64 + fr, col0 = u.pn * HALF + wc * 32 + 8 * fq;
; #pragma unroll
;         for (int ai = 0; ai < 2; ++ai)
; #pragma unroll
;             for (int m = 0; m < 4; ++m) { const int row = row0 + ai * HALF + m * 16;
;                 const float c = (float)__float_as_uint(pf[ai * 4 + m]) * (INV_D / SSQ_SCALE) + RMS_EPS_C, k1 = __builtin_amdgcn_rsqf(c) * -1.4426950408889634f;
;                 float o[8];
; #pragma unroll
;                 for (int e = 0; e < 8; ++e) { const float a = acc[ai][0][m][e >> 2][e & 3], b = acc[ai][1][m][e >> 2][e & 3];
;                     o[e] = (a * b) * __builtin_amdgcn_rcpf(__builtin_fmaf(__builtin_amdgcn_exp2f(a * k1), c, c)); }
;                 u32x4 w; w.x = cvt_pk_bf16(o[0], o[1]); w.y = cvt_pk_bf16(o[2], o[3]); w.z = cvt_pk_bf16(o[4], o[5]); w.w = cvt_pk_bf16(o[6], o[7]);
;                 *(u32x4*)(H + (size_t)row * ldh + col0) = w; }
; template <class Epi, class Sched, bool ALIGN_EPI = false, bool SP2 = false>
; __device__ __forceinline__ void gemm_phase(PG8_LAS unsigned char* lds, const Gemm g, const Sched& S, const Epi& E) {
;     ...
;             PG8_LDB(B0, 0, 0); PG8_LDB(B1, 0, 1); PG8_SCHED; PG8_LDA(At, 0, 0); PG8_STAGE(PG8_SA(1, 1), a1 + hstep, voffA);
.LBB0_570:
	v_add_u32_e32 v166, 0x10000, v153
	ds_read_b128 v[184:187], v166
	ds_read_b128 v[188:191], v166 offset:1024
	ds_read_b128 v[192:195], v166 offset:2048
	ds_read_b128 v[196:199], v166 offset:3072
	v_add_u32_e32 v167, 0x14000, v153
	ds_read_b128 v[200:203], v167
	ds_read_b128 v[204:207], v167 offset:1024
	ds_read_b128 v[208:211], v167 offset:2048
	ds_read_b128 v[212:215], v167 offset:3072
	ds_read_b128 v[216:219], v155
	ds_read_b128 v[220:223], v155 offset:1024
	ds_read_b128 v[224:227], v155 offset:2048
	ds_read_b128 v[228:231], v155 offset:3072
	ds_read_b128 v[232:235], v155 offset:4096
	ds_read_b128 v[236:239], v155 offset:5120
	ds_read_b128 v[240:243], v155 offset:6144
	ds_read_b128 v[244:247], v155 offset:7168
	s_waitcnt vmcnt(0)
	v_cvt_f32_u32_e32 v164, v164
	v_mul_f32_e32 v124, v128, v124
	v_mul_f32_e32 v116, v120, v116
	v_mul_f32_e32 v125, v129, v125
	v_fmamk_f32 v164, v164, 0x34800000, v141
	v_rsq_f32_e32 v165, v164
	v_mul_f32_e32 v117, v121, v117
	v_mul_f32_e32 v126, v130, v126
	v_mul_f32_e32 v118, v122, v118
	v_mul_f32_e32 v165, 0xbfb8aa3b, v165
	v_mul_f32_e32 v128, v165, v128
	v_mul_f32_e32 v120, v165, v120
	v_exp_f32_e32 v128, v128
	v_exp_f32_e32 v120, v120
	v_lshl_or_b32 v150, s17, 7, v154
	v_mul_f32_e32 v127, v131, v127
	v_fma_f32 v128, v128, v164, v164
	v_fma_f32 v120, v120, v164, v164
	v_rcp_f32_e32 v128, v128
	v_rcp_f32_e32 v120, v120
	v_mul_f32_e32 v119, v123, v119
	v_lshl_add_u32 v161, s16, 8, v152
	v_mul_f32_e32 v124, v128, v124
	v_mul_f32_e32 v128, v165, v129
	v_mul_f32_e32 v116, v120, v116
	v_mul_f32_e32 v120, v165, v121
	v_exp_f32_e32 v128, v128
	v_exp_f32_e32 v120, v120
	v_ashrrev_i32_e32 v151, 31, v150
	v_mul_f32_e32 v108, v112, v108
	v_fma_f32 v128, v128, v164, v164
	v_fma_f32 v120, v120, v164, v164
	v_rcp_f32_e32 v128, v128
	v_rcp_f32_e32 v120, v120
	v_mul_f32_e32 v100, v104, v100
	v_mul_f32_e32 v109, v113, v109
	v_mul_f32_e32 v125, v128, v125
	v_mul_f32_e32 v128, v165, v130
	v_mul_f32_e32 v117, v120, v117
	v_mul_f32_e32 v120, v165, v122
	v_exp_f32_e32 v128, v128
	v_exp_f32_e32 v120, v120
	v_mul_f32_e32 v110, v114, v110
	v_mul_f32_e32 v111, v115, v111
	v_fma_f32 v128, v128, v164, v164
	v_fma_f32 v120, v120, v164, v164
	v_rcp_f32_e32 v128, v128
	v_rcp_f32_e32 v120, v120
	v_mul_f32_e32 v92, v96, v92
	v_mul_f32_e32 v84, v88, v84
	v_mul_f32_e32 v126, v128, v126
	v_mul_f32_e32 v128, v165, v131
	v_mul_f32_e32 v118, v120, v118
	v_mul_f32_e32 v120, v165, v123
	v_exp_f32_e32 v128, v128
	v_exp_f32_e32 v120, v120
	v_mul_f32_e32 v93, v97, v93
	v_mul_f32_e32 v94, v98, v94
	v_fma_f32 v128, v128, v164, v164
	v_fmac_f32_e32 v164, v120, v164
	v_rcp_f32_e32 v128, v128
	v_rcp_f32_e32 v120, v164
	v_mul_f32_e32 v95, v99, v95
	v_mul_f32_e32 v76, v80, v76
	v_mul_f32_e32 v127, v128, v127
	v_mul_f32_e32 v119, v120, v119
	v_cvt_pk_bf16_f32 v120, v124, v125
	v_cvt_pk_bf16_f32 v121, v126, v127
	v_cvt_pk_bf16_f32 v122, v116, v117
	v_mov_b64_e32 v[116:117], s[48:49]
	v_cvt_pk_bf16_f32 v123, v118, v119
	v_mad_i64_i32 v[124:125], s[16:17], v161, s58, v[116:117]
	v_lshlrev_b64 v[118:119], 1, v[150:151]
	v_lshl_add_u64 v[124:125], v[124:125], 0, v[118:119]
	global_store_dwordx4 v[124:125], v[120:123], off
	v_mul_f32_e32 v68, v72, v68
	v_mul_f32_e32 v77, v81, v77
	v_cvt_f32_u32_e32 v120, v163
	v_mul_f32_e32 v78, v82, v78
	v_mul_f32_e32 v79, v83, v79
	v_mul_f32_e32 v60, v64, v60
	v_fmamk_f32 v120, v120, 0x34800000, v141
	v_rsq_f32_e32 v121, v120
	v_mul_f32_e32 v52, v56, v52
	v_mul_f32_e32 v61, v65, v61
	v_mul_f32_e32 v62, v66, v62
	v_mul_f32_e32 v121, 0xbfb8aa3b, v121
	v_mul_f32_e32 v112, v121, v112
	v_mul_f32_e32 v104, v121, v104
	v_exp_f32_e32 v112, v112
	v_exp_f32_e32 v104, v104
	v_mul_f32_e32 v63, v67, v63
	v_mul_f32_e32 v44, v48, v44
	v_fma_f32 v112, v112, v120, v120
	v_fma_f32 v104, v104, v120, v120
	v_rcp_f32_e32 v112, v112
	v_rcp_f32_e32 v104, v104
	v_mul_f32_e32 v36, v40, v36
	v_mul_f32_e32 v45, v49, v45
	v_mul_f32_e32 v108, v112, v108
	v_mul_f32_e32 v112, v121, v113
	v_mul_f32_e32 v104, v104, v100
	v_mul_f32_e32 v100, v105, v101
	v_mul_f32_e32 v101, v121, v105
	v_exp_f32_e32 v112, v112
	v_exp_f32_e32 v101, v101
	v_mul_f32_e32 v46, v50, v46
	v_mul_f32_e32 v47, v51, v47
	v_fma_f32 v112, v112, v120, v120
	v_fma_f32 v101, v101, v120, v120
	v_rcp_f32_e32 v112, v112
	v_rcp_f32_e32 v101, v101
	v_mul_f32_e32 v28, v32, v28
	v_mul_f32_e32 v20, v24, v20
	v_mul_f32_e32 v109, v112, v109
	v_mul_f32_e32 v112, v121, v114
	v_mul_f32_e32 v105, v101, v100
	v_mul_f32_e32 v101, v121, v106
	v_exp_f32_e32 v112, v112
	v_exp_f32_e32 v101, v101
	v_mul_f32_e32 v100, v106, v102
	v_mul_f32_e32 v29, v33, v29
	v_fma_f32 v112, v112, v120, v120
	v_fma_f32 v101, v101, v120, v120
	v_rcp_f32_e32 v112, v112
	v_rcp_f32_e32 v101, v101
	v_mul_f32_e32 v30, v34, v30
	v_mul_f32_e32 v31, v35, v31
	v_mul_f32_e32 v110, v112, v110
	v_mul_f32_e32 v112, v121, v115
	v_mul_f32_e32 v106, v101, v100
	v_mul_f32_e32 v101, v121, v107
	v_exp_f32_e32 v112, v112
	v_exp_f32_e32 v101, v101
	v_mul_f32_e32 v100, v107, v103
	v_or_b32_e32 v107, 16, v161
	v_fma_f32 v112, v112, v120, v120
	v_fmac_f32_e32 v120, v101, v120
	v_rcp_f32_e32 v112, v112
	v_rcp_f32_e32 v101, v120
	v_mul_f32_e32 v12, v16, v12
	v_mul_f32_e32 v4, v8, v4
	v_mul_f32_e32 v111, v112, v111
	v_mul_f32_e32 v103, v101, v100
	v_cvt_pk_bf16_f32 v100, v108, v109
	v_cvt_pk_bf16_f32 v101, v110, v111
	v_cvt_pk_bf16_f32 v102, v104, v105
	v_mad_i64_i32 v[104:105], s[16:17], v107, s58, v[116:117]
	v_lshl_add_u64 v[104:105], v[104:105], 0, v[118:119]
	v_cvt_pk_bf16_f32 v103, v106, v103
	global_store_dwordx4 v[104:105], v[100:103], off
	v_mul_f32_e32 v13, v17, v13
	v_mul_f32_e32 v14, v18, v14
	v_cvt_f32_u32_e32 v100, v162
; __device__ __forceinline__ unsigned cvt_pk_bf16(float lo, float hi) { unsigned r; asm volatile("v_cvt_pk_bf16_f32 %0, %1, %2" : "=v"(r) : "v"(lo), "v"(hi)); return r; }
;     __device__ __forceinline__ void operator()(const f32x4 (&acc)[2][2][4][2], const Unit& u, int wr, int wc, int fr, int fq, const float (&pf)[8]) const {
;         const int row0 = u.pm * BM + wr * 64 + fr, col0 = u.pn * HALF + wc * 32 + 8 * fq;
; #pragma unroll
;         for (int ai = 0; ai < 2; ++ai)
; #pragma unroll
;             for (int m = 0; m < 4; ++m) { const int row = row0 + ai * HALF + m * 16;
;                 const float c = (float)__float_as_uint(pf[ai * 4 + m]) * (INV_D / SSQ_SCALE) + RMS_EPS_C, k1 = __builtin_amdgcn_rsqf(c) * -1.4426950408889634f;
;                 float o[8];
; #pragma unroll
;                 for (int e = 0; e < 8; ++e) { const float a = acc[ai][0][m][e >> 2][e & 3], b = acc[ai][1][m][e >> 2][e & 3];
;                     o[e] = (a * b) * __builtin_amdgcn_rcpf(__builtin_fmaf(__builtin_amdgcn_exp2f(a * k1), c, c)); }
;                 u32x4 w; w.x = cvt_pk_bf16(o[0], o[1]); w.y = cvt_pk_bf16(o[2], o[3]); w.z = cvt_pk_bf16(o[4], o[5]); w.w = cvt_pk_bf16(o[6], o[7]);
;                 *(u32x4*)(H + (size_t)row * ldh + col0) = w; }
	v_mul_f32_e32 v15, v19, v15
	s_andn2_b64 vcc, exec, s[2:3]
	v_fmamk_f32 v100, v100, 0x34800000, v141
	v_rsq_f32_e32 v101, v100
	s_nop 0
	v_mul_f32_e32 v101, 0xbfb8aa3b, v101
	v_mul_f32_e32 v96, v101, v96
	v_mul_f32_e32 v88, v101, v88
	v_exp_f32_e32 v96, v96
	v_exp_f32_e32 v88, v88
	v_fma_f32 v96, v96, v100, v100
	v_fma_f32 v88, v88, v100, v100
	v_rcp_f32_e32 v96, v96
	v_rcp_f32_e32 v88, v88
	v_mul_f32_e32 v92, v96, v92
	v_mul_f32_e32 v96, v101, v97
	v_mul_f32_e32 v88, v88, v84
	v_mul_f32_e32 v84, v89, v85
	v_mul_f32_e32 v85, v101, v89
	v_exp_f32_e32 v96, v96
	v_exp_f32_e32 v85, v85
	v_fma_f32 v96, v96, v100, v100
	v_fma_f32 v85, v85, v100, v100
	v_rcp_f32_e32 v96, v96
	v_rcp_f32_e32 v85, v85
	v_mul_f32_e32 v93, v96, v93
	v_mul_f32_e32 v96, v101, v98
	v_mul_f32_e32 v89, v85, v84
	v_mul_f32_e32 v85, v101, v90
	v_exp_f32_e32 v96, v96
	v_exp_f32_e32 v85, v85
	v_mul_f32_e32 v84, v90, v86
	v_fma_f32 v96, v96, v100, v100
	v_fma_f32 v85, v85, v100, v100
	v_rcp_f32_e32 v96, v96
	v_rcp_f32_e32 v85, v85
	v_mul_f32_e32 v94, v96, v94
	v_mul_f32_e32 v96, v101, v99
	v_mul_f32_e32 v90, v85, v84
	v_mul_f32_e32 v85, v101, v91
	v_exp_f32_e32 v96, v96
	v_exp_f32_e32 v85, v85
	v_mul_f32_e32 v84, v91, v87
	v_or_b32_e32 v91, 32, v161
	v_fma_f32 v96, v96, v100, v100
	v_fmac_f32_e32 v100, v85, v100
	v_rcp_f32_e32 v96, v96
	v_rcp_f32_e32 v85, v100
	v_mul_f32_e32 v95, v96, v95
	v_mul_f32_e32 v87, v85, v84
	v_cvt_pk_bf16_f32 v84, v92, v93
	v_cvt_pk_bf16_f32 v85, v94, v95
	v_cvt_pk_bf16_f32 v86, v88, v89
	v_mad_i64_i32 v[88:89], s[16:17], v91, s58, v[116:117]
	v_lshl_add_u64 v[88:89], v[88:89], 0, v[118:119]
	v_cvt_pk_bf16_f32 v87, v90, v87
	global_store_dwordx4 v[88:89], v[84:87], off
	s_nop 1
	v_cvt_f32_u32_e32 v84, v160
	v_fmamk_f32 v84, v84, 0x34800000, v141
	v_rsq_f32_e32 v85, v84
	s_nop 0
	v_mul_f32_e32 v85, 0xbfb8aa3b, v85
	v_mul_f32_e32 v80, v85, v80
	v_mul_f32_e32 v72, v85, v72
	v_exp_f32_e32 v80, v80
	v_exp_f32_e32 v72, v72
	v_fma_f32 v80, v80, v84, v84
	v_fma_f32 v72, v72, v84, v84
	v_rcp_f32_e32 v80, v80
	v_rcp_f32_e32 v72, v72
	v_mul_f32_e32 v76, v80, v76
	v_mul_f32_e32 v80, v85, v81
	v_mul_f32_e32 v72, v72, v68
	v_mul_f32_e32 v68, v73, v69
	v_mul_f32_e32 v69, v85, v73
	v_exp_f32_e32 v80, v80
	v_exp_f32_e32 v69, v69
	v_fma_f32 v80, v80, v84, v84
	v_fma_f32 v69, v69, v84, v84
	v_rcp_f32_e32 v80, v80
	v_rcp_f32_e32 v69, v69
	v_mul_f32_e32 v77, v80, v77
	v_mul_f32_e32 v80, v85, v82
	v_mul_f32_e32 v73, v69, v68
	v_mul_f32_e32 v69, v85, v74
	v_exp_f32_e32 v80, v80
	v_exp_f32_e32 v69, v69
	v_mul_f32_e32 v68, v74, v70
	v_fma_f32 v80, v80, v84, v84
	v_fma_f32 v69, v69, v84, v84
	v_rcp_f32_e32 v80, v80
	v_rcp_f32_e32 v69, v69
	v_mul_f32_e32 v78, v80, v78
	v_mul_f32_e32 v80, v85, v83
	v_mul_f32_e32 v74, v69, v68
	v_mul_f32_e32 v69, v85, v75
	v_exp_f32_e32 v80, v80
	v_exp_f32_e32 v69, v69
	v_mul_f32_e32 v68, v75, v71
	v_or_b32_e32 v75, 48, v161
	v_fma_f32 v80, v80, v84, v84
	v_fmac_f32_e32 v84, v69, v84
	v_rcp_f32_e32 v80, v80
	v_rcp_f32_e32 v69, v84
	v_mul_f32_e32 v79, v80, v79
	v_mul_f32_e32 v71, v69, v68
	v_cvt_pk_bf16_f32 v68, v76, v77
	v_cvt_pk_bf16_f32 v69, v78, v79
	v_cvt_pk_bf16_f32 v70, v72, v73
	v_mad_i64_i32 v[72:73], s[16:17], v75, s58, v[116:117]
	v_lshl_add_u64 v[72:73], v[72:73], 0, v[118:119]
	v_cvt_pk_bf16_f32 v71, v74, v71
	global_store_dwordx4 v[72:73], v[68:71], off
	s_nop 1
	v_cvt_f32_u32_e32 v69, v159
	v_add_u32_e32 v68, 0x80, v161
	v_fmamk_f32 v69, v69, 0x34800000, v141
	v_rsq_f32_e32 v70, v69
	s_nop 0
	v_mul_f32_e32 v70, 0xbfb8aa3b, v70
	v_mul_f32_e32 v64, v70, v64
	v_mul_f32_e32 v56, v70, v56
	v_exp_f32_e32 v64, v64
	v_exp_f32_e32 v56, v56
	v_fma_f32 v64, v64, v69, v69
	v_fma_f32 v56, v56, v69, v69
	v_rcp_f32_e32 v64, v64
	v_rcp_f32_e32 v56, v56
	v_mul_f32_e32 v60, v64, v60
	v_mul_f32_e32 v64, v70, v65
	v_mul_f32_e32 v56, v56, v52
	v_mul_f32_e32 v52, v57, v53
	v_mul_f32_e32 v53, v70, v57
	v_exp_f32_e32 v64, v64
	v_exp_f32_e32 v53, v53
	v_fma_f32 v64, v64, v69, v69
	v_fma_f32 v53, v53, v69, v69
	v_rcp_f32_e32 v64, v64
	v_rcp_f32_e32 v53, v53
	v_mul_f32_e32 v61, v64, v61
	v_mul_f32_e32 v64, v70, v66
	v_mul_f32_e32 v57, v53, v52
	v_mul_f32_e32 v53, v70, v58
	v_exp_f32_e32 v64, v64
	v_exp_f32_e32 v53, v53
	v_mul_f32_e32 v52, v58, v54
	v_fma_f32 v64, v64, v69, v69
	v_fma_f32 v53, v53, v69, v69
	v_rcp_f32_e32 v64, v64
	v_rcp_f32_e32 v53, v53
	v_mul_f32_e32 v62, v64, v62
	v_mul_f32_e32 v64, v70, v67
	v_mul_f32_e32 v58, v53, v52
	v_mul_f32_e32 v53, v70, v59
	v_exp_f32_e32 v64, v64
	v_exp_f32_e32 v53, v53
	v_mul_f32_e32 v52, v59, v55
	v_fma_f32 v64, v64, v69, v69
	v_fmac_f32_e32 v69, v53, v69
	v_rcp_f32_e32 v64, v64
	v_rcp_f32_e32 v53, v69
	v_mul_f32_e32 v63, v64, v63
	v_mul_f32_e32 v55, v53, v52
	v_cvt_pk_bf16_f32 v52, v60, v61
	v_cvt_pk_bf16_f32 v53, v62, v63
	v_cvt_pk_bf16_f32 v54, v56, v57
	v_mad_i64_i32 v[56:57], s[16:17], v68, s58, v[116:117]
	v_lshl_add_u64 v[56:57], v[56:57], 0, v[118:119]
	v_cvt_pk_bf16_f32 v55, v58, v55
	global_store_dwordx4 v[56:57], v[52:55], off
	s_nop 1
	v_cvt_f32_u32_e32 v52, v158
	v_fmamk_f32 v52, v52, 0x34800000, v141
	v_rsq_f32_e32 v53, v52
	s_nop 0
	v_mul_f32_e32 v53, 0xbfb8aa3b, v53
	v_mul_f32_e32 v48, v53, v48
	v_mul_f32_e32 v40, v53, v40
	v_exp_f32_e32 v48, v48
	v_exp_f32_e32 v40, v40
; __device__ __forceinline__ unsigned cvt_pk_bf16(float lo, float hi) { unsigned r; asm volatile("v_cvt_pk_bf16_f32 %0, %1, %2" : "=v"(r) : "v"(lo), "v"(hi)); return r; }
; #define PG8_BAR __builtin_amdgcn_s_barrier()
;     __device__ __forceinline__ void operator()(const f32x4 (&acc)[2][2][4][2], const Unit& u, int wr, int wc, int fr, int fq, const float (&pf)[8]) const {
;         const int row0 = u.pm * BM + wr * 64 + fr, col0 = u.pn * HALF + wc * 32 + 8 * fq;
; #pragma unroll
;         for (int ai = 0; ai < 2; ++ai)
; #pragma unroll
;             for (int m = 0; m < 4; ++m) { const int row = row0 + ai * HALF + m * 16;
;                 const float c = (float)__float_as_uint(pf[ai * 4 + m]) * (INV_D / SSQ_SCALE) + RMS_EPS_C, k1 = __builtin_amdgcn_rsqf(c) * -1.4426950408889634f;
;                 float o[8];
; #pragma unroll
;                 for (int e = 0; e < 8; ++e) { const float a = acc[ai][0][m][e >> 2][e & 3], b = acc[ai][1][m][e >> 2][e & 3];
;                     o[e] = (a * b) * __builtin_amdgcn_rcpf(__builtin_fmaf(__builtin_amdgcn_exp2f(a * k1), c, c)); }
;                 u32x4 w; w.x = cvt_pk_bf16(o[0], o[1]); w.y = cvt_pk_bf16(o[2], o[3]); w.z = cvt_pk_bf16(o[4], o[5]); w.w = cvt_pk_bf16(o[6], o[7]);
;                 *(u32x4*)(H + (size_t)row * ldh + col0) = w; }
; template <class Epi, class Sched, bool ALIGN_EPI = false, bool SP2 = false>
; __device__ __forceinline__ void gemm_phase(PG8_LAS unsigned char* lds, const Gemm g, const Sched& S, const Epi& E) {
;     ...
;         if (!has_next) break;
; #pragma unroll
;         for (int a = 0; a < 2; ++a)
; #pragma unroll
;             for (int b = 0; b < 2; ++b)
; #pragma unroll
;                 for (int m = 0; m < 4; ++m)
; #pragma unroll
;                     for (int n = 0; n < 2; ++n) acc[a][b][m][n] = (f32x4){0.f, 0.f, 0.f, 0.f};
;         cur = nxt; cA = nA; cB = nB; ++ui;
;         if constexpr (Epi::PREFETCH) E.prefetch(cur, wr, fr, pf);
;         if constexpr (ALIGN_EPI) { if (wr == 1) PG8_BAR; }
	v_fma_f32 v48, v48, v52, v52
	v_fma_f32 v40, v40, v52, v52
	v_rcp_f32_e32 v48, v48
	v_rcp_f32_e32 v40, v40
	v_mul_f32_e32 v44, v48, v44
	v_mul_f32_e32 v48, v53, v49
	v_mul_f32_e32 v40, v40, v36
	v_mul_f32_e32 v36, v41, v37
	v_mul_f32_e32 v37, v53, v41
	v_exp_f32_e32 v48, v48
	v_exp_f32_e32 v37, v37
	v_fma_f32 v48, v48, v52, v52
	v_fma_f32 v37, v37, v52, v52
	v_rcp_f32_e32 v48, v48
	v_rcp_f32_e32 v37, v37
	v_mul_f32_e32 v45, v48, v45
	v_mul_f32_e32 v48, v53, v50
	v_mul_f32_e32 v41, v37, v36
	v_mul_f32_e32 v37, v53, v42
	v_exp_f32_e32 v48, v48
	v_exp_f32_e32 v37, v37
	v_mul_f32_e32 v36, v42, v38
	v_fma_f32 v48, v48, v52, v52
	v_fma_f32 v37, v37, v52, v52
	v_rcp_f32_e32 v48, v48
	v_rcp_f32_e32 v37, v37
	v_mul_f32_e32 v46, v48, v46
	v_mul_f32_e32 v48, v53, v51
	v_mul_f32_e32 v42, v37, v36
	v_mul_f32_e32 v37, v53, v43
	v_exp_f32_e32 v48, v48
	v_exp_f32_e32 v37, v37
	v_mul_f32_e32 v36, v43, v39
	v_add_u32_e32 v43, 0x90, v161
	v_fma_f32 v48, v48, v52, v52
	v_fmac_f32_e32 v52, v37, v52
	v_rcp_f32_e32 v48, v48
	v_rcp_f32_e32 v37, v52
	v_mul_f32_e32 v47, v48, v47
	v_mul_f32_e32 v39, v37, v36
	v_cvt_pk_bf16_f32 v36, v44, v45
	v_cvt_pk_bf16_f32 v37, v46, v47
	v_cvt_pk_bf16_f32 v38, v40, v41
	v_mad_i64_i32 v[40:41], s[16:17], v43, s58, v[116:117]
	v_lshl_add_u64 v[40:41], v[40:41], 0, v[118:119]
	v_cvt_pk_bf16_f32 v39, v42, v39
	global_store_dwordx4 v[40:41], v[36:39], off
	s_nop 1
	v_cvt_f32_u32_e32 v36, v157
	v_fmamk_f32 v36, v36, 0x34800000, v141
	v_rsq_f32_e32 v37, v36
	s_nop 0
	v_mul_f32_e32 v37, 0xbfb8aa3b, v37
	v_mul_f32_e32 v32, v37, v32
	v_mul_f32_e32 v24, v37, v24
	v_exp_f32_e32 v32, v32
	v_exp_f32_e32 v24, v24
	v_fma_f32 v32, v32, v36, v36
	v_fma_f32 v24, v24, v36, v36
	v_rcp_f32_e32 v32, v32
	v_rcp_f32_e32 v24, v24
	v_mul_f32_e32 v28, v32, v28
	v_mul_f32_e32 v32, v37, v33
	v_mul_f32_e32 v24, v24, v20
	v_mul_f32_e32 v20, v25, v21
	v_mul_f32_e32 v21, v37, v25
	v_exp_f32_e32 v32, v32
	v_exp_f32_e32 v21, v21
	v_fma_f32 v32, v32, v36, v36
	v_fma_f32 v21, v21, v36, v36
	v_rcp_f32_e32 v32, v32
	v_rcp_f32_e32 v21, v21
	v_mul_f32_e32 v29, v32, v29
	v_mul_f32_e32 v32, v37, v34
	v_mul_f32_e32 v25, v21, v20
	v_mul_f32_e32 v21, v37, v26
	v_exp_f32_e32 v32, v32
	v_exp_f32_e32 v21, v21
	v_mul_f32_e32 v20, v26, v22
	v_fma_f32 v32, v32, v36, v36
	v_fma_f32 v21, v21, v36, v36
	v_rcp_f32_e32 v32, v32
	v_rcp_f32_e32 v21, v21
	v_mul_f32_e32 v30, v32, v30
	v_mul_f32_e32 v32, v37, v35
	v_mul_f32_e32 v26, v21, v20
	v_mul_f32_e32 v21, v37, v27
	v_exp_f32_e32 v32, v32
	v_exp_f32_e32 v21, v21
	v_mul_f32_e32 v20, v27, v23
	v_add_u32_e32 v27, 0xa0, v161
	v_fma_f32 v32, v32, v36, v36
	v_fmac_f32_e32 v36, v21, v36
	v_rcp_f32_e32 v32, v32
	v_rcp_f32_e32 v21, v36
	v_mul_f32_e32 v31, v32, v31
	v_mul_f32_e32 v23, v21, v20
	v_cvt_pk_bf16_f32 v20, v28, v29
	v_cvt_pk_bf16_f32 v21, v30, v31
	v_cvt_pk_bf16_f32 v22, v24, v25
	v_mad_i64_i32 v[24:25], s[16:17], v27, s58, v[116:117]
	v_lshl_add_u64 v[24:25], v[24:25], 0, v[118:119]
	v_cvt_pk_bf16_f32 v23, v26, v23
	global_store_dwordx4 v[24:25], v[20:23], off
	s_nop 1
	v_cvt_f32_u32_e32 v20, v156
	v_fmamk_f32 v20, v20, 0x34800000, v141
	v_rsq_f32_e32 v21, v20
	s_nop 0
	v_mul_f32_e32 v21, 0xbfb8aa3b, v21
	v_mul_f32_e32 v16, v21, v16
	v_mul_f32_e32 v8, v21, v8
	v_exp_f32_e32 v16, v16
	v_exp_f32_e32 v8, v8
	v_fma_f32 v16, v16, v20, v20
	v_fma_f32 v8, v8, v20, v20
	v_rcp_f32_e32 v16, v16
	v_rcp_f32_e32 v8, v8
	v_mul_f32_e32 v12, v16, v12
	v_mul_f32_e32 v16, v21, v17
	v_mul_f32_e32 v8, v8, v4
	v_mul_f32_e32 v4, v9, v5
	v_mul_f32_e32 v5, v21, v9
	v_exp_f32_e32 v16, v16
	v_exp_f32_e32 v5, v5
	v_fma_f32 v16, v16, v20, v20
	v_fma_f32 v5, v5, v20, v20
	v_rcp_f32_e32 v16, v16
	v_rcp_f32_e32 v5, v5
	v_mul_f32_e32 v13, v16, v13
	v_mul_f32_e32 v16, v21, v18
	v_mul_f32_e32 v9, v5, v4
	v_mul_f32_e32 v5, v21, v10
	v_exp_f32_e32 v16, v16
	v_exp_f32_e32 v5, v5
	v_mul_f32_e32 v4, v10, v6
	v_fma_f32 v16, v16, v20, v20
	v_fma_f32 v5, v5, v20, v20
	v_rcp_f32_e32 v16, v16
	v_rcp_f32_e32 v5, v5
	v_mul_f32_e32 v14, v16, v14
	v_mul_f32_e32 v16, v21, v19
	v_mul_f32_e32 v10, v5, v4
	v_mul_f32_e32 v5, v21, v11
	v_exp_f32_e32 v16, v16
	v_exp_f32_e32 v5, v5
	v_mul_f32_e32 v4, v11, v7
	v_add_u32_e32 v11, 0xb0, v161
	v_fma_f32 v16, v16, v20, v20
	v_fmac_f32_e32 v20, v5, v20
	v_rcp_f32_e32 v16, v16
	v_rcp_f32_e32 v5, v20
	v_mul_f32_e32 v15, v16, v15
	v_mul_f32_e32 v7, v5, v4
	v_cvt_pk_bf16_f32 v4, v12, v13
	v_cvt_pk_bf16_f32 v5, v14, v15
	v_cvt_pk_bf16_f32 v6, v8, v9
	v_mad_i64_i32 v[8:9], s[16:17], v11, s58, v[116:117]
	v_lshl_add_u64 v[8:9], v[8:9], 0, v[118:119]
	s_mov_b64 s[16:17], -1
	v_cvt_pk_bf16_f32 v7, v10, v7
	global_store_dwordx4 v[8:9], v[4:7], off
	s_cbranch_vccnz .LBB0_563
	s_nop 0
	v_lshl_add_u32 v4, s10, 8, v152
	v_ashrrev_i32_e32 v5, 31, v4
	v_lshl_add_u64 v[4:5], v[4:5], 2, s[0:1]
	global_load_dword v164, v[4:5], off
	global_load_dword v163, v[4:5], off offset:64
	global_load_dword v162, v[4:5], off offset:128
	global_load_dword v160, v[4:5], off offset:192
	global_load_dword v159, v[4:5], off offset:512
	global_load_dword v158, v[4:5], off offset:576
	global_load_dword v157, v[4:5], off offset:640
	global_load_dword v156, v[4:5], off offset:704
	s_andn2_b64 vcc, exec, s[4:5]
	s_cbranch_vccnz .LBB0_562
	s_barrier
	s_branch .LBB0_562
